# LayerNorm work queue: next item requested by thread 0 right before the rows of the current one (prefetch in v250)
# baseline (speedup 1.0000x reference)
.LBB0_54:
	s_mov_b32 s100, 0
	v_readlane_b32 s10, v252, 54
	v_readlane_b32 s11, v252, 55
	v_readlane_b32 s16, v251, 1
	s_lshl_b64 s[12:13], s[10:11], 2
	v_readlane_b32 s18, v251, 3
	v_readlane_b32 s19, v251, 4
	s_add_u32 s10, s18, s12
	s_addc_u32 s11, s19, s13
	v_readlane_b32 s17, v251, 2
	s_add_u32 s12, s16, s12
	s_addc_u32 s13, s17, s13
	v_readlane_b32 s16, v252, 56
	v_readlane_b32 s17, v252, 57
	s_lshl_b64 s[16:17], s[16:17], 2
	s_add_u32 s16, s0, s16
	s_addc_u32 s17, s1, s17
	s_add_u32 s16, s16, 0x23f9a210
	s_addc_u32 s17, s17, 0
	s_add_u32 s8, s8, 0x1000
	s_addc_u32 s9, s9, 0
	s_mov_b64 s[18:19], 0
	v_readlane_b32 s20, v251, 5
	v_readlane_b32 s21, v251, 6
	v_readlane_b32 s22, v251, 7
	v_readlane_b32 s23, v251, 8
	v_readlane_b32 s24, v251, 9
	v_readlane_b32 s25, v251, 10
	v_readlane_b32 s26, v251, 11
	v_readlane_b32 s27, v251, 12
	v_readlane_b32 s28, v251, 13
	v_readlane_b32 s29, v251, 14
	v_readlane_b32 s30, v251, 15
	v_readlane_b32 s31, v251, 16
	s_branch .LBB0_56

.LBB0_56:
	s_waitcnt lgkmcnt(0)
	s_barrier
	s_mov_b64 s[20:21], exec
	v_readlane_b32 s22, v251, 19
	v_readlane_b32 s23, v251, 20
	s_and_b64 s[22:23], s[20:21], s[22:23]
	s_mov_b64 exec, s[22:23]
	s_cbranch_execz .LBB0_58
	s_waitcnt vmcnt(0)
	s_cmp_eq_u32 s100, 0
	s_cbranch_scc1 .Llnq_atomic_A
	v_mov_b32_e32 v0, v250
	s_branch .Llnq_have_A
.Llnq_atomic_A:
	v_mov_b64_e32 v[2:3], s[16:17]
	flat_atomic_add v0, v[2:3], v213 sc0
.Llnq_have_A:
	s_mov_b64 s[22:23], src_shared_base
	s_add_i32 s22, 0, 0x22ff0
	s_cmp_lg_u32 s22, -1
	s_cselect_b32 s22, s22, 0
	s_cselect_b32 s23, s23, 0
	v_mov_b32_e32 v2, s22
	v_mov_b32_e32 v3, s23
	s_waitcnt vmcnt(0) lgkmcnt(0)
	flat_store_dword v[2:3], v0 sc0 sc1
	s_waitcnt vmcnt(0)

.LBB0_64:
	v_readlane_b32 s74, v251, 19
	v_readlane_b32 s75, v251, 20
	s_mov_b64 s[78:79], exec
	s_nop 3
	s_and_b64 exec, exec, s[74:75]
	global_atomic_add v250, v1, v213, s[16:17] sc0
	s_mov_b64 exec, s[78:79]
	s_mov_b32 s100, 1
	v_lshlrev_b32_e32 v212, 4, v219
	v_lshlrev_b32_e32 v214, 3, v219
	v_readfirstlane_b32 s42, v32
	v_readfirstlane_b32 s43, v33
	v_readfirstlane_b32 s66, v30
	v_readfirstlane_b32 s67, v31
	global_load_dwordx4 v[184:187], v[26:27], off offset:0
	global_load_dwordx4 v[188:191], v[26:27], off offset:1024
	global_load_dwordx4 v[192:195], v[26:27], off offset:2048
	global_load_dwordx4 v[196:199], v[26:27], off offset:3072
	global_load_dwordx4 v[200:203], v[28:29], off offset:0
	global_load_dwordx4 v[204:207], v[28:29], off offset:1024
	global_load_dwordx4 v[226:229], v[28:29], off offset:2048
	global_load_dwordx4 v[230:233], v[28:29], off offset:3072
	s_sub_u32 s42, s42, 0x1000
	s_subb_u32 s43, s43, 0
	global_load_dwordx4 v[2:5], v212, s[42:43] offset:0 sc1
	global_load_dwordx4 v[6:9], v212, s[42:43] offset:1024 sc1
	global_load_dwordx4 v[10:13], v212, s[42:43] offset:2048 sc1
	global_load_dwordx4 v[14:17], v212, s[42:43] offset:3072 sc1
	s_add_u32 s44, s42, 0x1000
	s_addc_u32 s45, s43, 0
	global_load_dwordx4 v[18:21], v212, s[44:45] offset:0 sc1
	global_load_dwordx4 v[22:25], v212, s[44:45] offset:1024 sc1
	global_load_dwordx4 v[34:37], v212, s[44:45] offset:2048 sc1
	global_load_dwordx4 v[38:41], v212, s[44:45] offset:3072 sc1
	s_add_u32 s46, s44, 0x1000
	s_addc_u32 s47, s45, 0
	global_load_dwordx4 v[44:47], v212, s[46:47] offset:0 sc1
	global_load_dwordx4 v[48:51], v212, s[46:47] offset:1024 sc1
	global_load_dwordx4 v[52:55], v212, s[46:47] offset:2048 sc1
	global_load_dwordx4 v[56:59], v212, s[46:47] offset:3072 sc1
	s_add_u32 s48, s46, 0x1000
	s_addc_u32 s49, s47, 0
	global_load_dwordx4 v[60:63], v212, s[48:49] offset:0 sc1
	global_load_dwordx4 v[64:67], v212, s[48:49] offset:1024 sc1
	global_load_dwordx4 v[94:97], v212, s[48:49] offset:2048 sc1
	global_load_dwordx4 v[98:101], v212, s[48:49] offset:3072 sc1
	s_add_u32 s50, s48, 0x1000
	s_addc_u32 s51, s49, 0
	global_load_dwordx4 v[102:105], v212, s[50:51] offset:0 sc1
	global_load_dwordx4 v[106:109], v212, s[50:51] offset:1024 sc1
	global_load_dwordx4 v[110:113], v212, s[50:51] offset:2048 sc1
	global_load_dwordx4 v[114:117], v212, s[50:51] offset:3072 sc1
	s_add_u32 s52, s50, 0x1000
	s_addc_u32 s53, s51, 0
	global_load_dwordx4 v[118:121], v212, s[52:53] offset:0 sc1
	global_load_dwordx4 v[122:125], v212, s[52:53] offset:1024 sc1
	global_load_dwordx4 v[144:147], v212, s[52:53] offset:2048 sc1
	global_load_dwordx4 v[148:151], v212, s[52:53] offset:3072 sc1
	s_add_u32 s62, s52, 0x1000
	s_addc_u32 s63, s53, 0
	global_load_dwordx4 v[152:155], v212, s[62:63] offset:0 sc1
	global_load_dwordx4 v[156:159], v212, s[62:63] offset:1024 sc1
	global_load_dwordx4 v[160:163], v212, s[62:63] offset:2048 sc1
	global_load_dwordx4 v[164:167], v212, s[62:63] offset:3072 sc1
	s_add_u32 s64, s62, 0x1000
	s_addc_u32 s65, s63, 0
	global_load_dwordx4 v[168:171], v212, s[64:65] offset:0 sc1
	global_load_dwordx4 v[172:175], v212, s[64:65] offset:1024 sc1
	global_load_dwordx4 v[176:179], v212, s[64:65] offset:2048 sc1
	global_load_dwordx4 v[180:183], v212, s[64:65] offset:3072 sc1
	s_add_u32 s66, s66, 0x1f80000
	s_addc_u32 s67, s67, 0
	s_add_u32 s68, s66, 0x1000
	s_addc_u32 s69, s67, 0
	s_add_u32 s70, s68, 0x1000
	s_addc_u32 s71, s69, 0
	s_add_u32 s72, s70, 0x1000
	s_addc_u32 s73, s71, 0
	s_waitcnt vmcnt(28)
	v_pk_add_f32 v[76:77], v[2:3], v[4:5]
	v_pk_add_f32 v[136:137], v[6:7], v[8:9]
	v_pk_add_f32 v[138:139], v[10:11], v[12:13]
	v_pk_add_f32 v[208:209], v[14:15], v[16:17]
	v_pk_add_f32 v[76:77], v[76:77], v[136:137]
	v_pk_add_f32 v[138:139], v[138:139], v[208:209]
	v_pk_add_f32 v[76:77], v[76:77], v[138:139]
	v_add_f32_e32 v131, v76, v77
	s_nop 1
	v_add_f32_dpp v131, v131, v131 quad_perm:[1,0,3,2] row_mask:0xf bank_mask:0xf bound_ctrl:1
	s_nop 1
	v_add_f32_dpp v131, v131, v131 quad_perm:[2,3,0,1] row_mask:0xf bank_mask:0xf bound_ctrl:1
	s_nop 1
	v_add_f32_dpp v131, v131, v131 row_half_mirror row_mask:0xf bank_mask:0xf bound_ctrl:1
	s_nop 1
	v_add_f32_dpp v131, v131, v131 row_mirror row_mask:0xf bank_mask:0xf bound_ctrl:1
	s_nop 1
	v_readlane_b32 s56, v131, 0
	v_readlane_b32 s57, v131, 16
	v_readlane_b32 s58, v131, 32
	v_readlane_b32 s59, v131, 48
	v_mov_b32_e32 v222, s57
	v_mov_b32_e32 v223, s59
	v_add_f32_e32 v222, s56, v222
	v_add_f32_e32 v223, s58, v223
	v_add_f32_e32 v131, v222, v223
	v_mul_f32_e32 v216, 0x3a800000, v131
	v_pk_add_f32 v[2:3], v[2:3], v[216:217] op_sel_hi:[1,0] neg_lo:[0,1] neg_hi:[0,1]
	v_pk_add_f32 v[4:5], v[4:5], v[216:217] op_sel_hi:[1,0] neg_lo:[0,1] neg_hi:[0,1]
	v_pk_add_f32 v[6:7], v[6:7], v[216:217] op_sel_hi:[1,0] neg_lo:[0,1] neg_hi:[0,1]
	v_pk_add_f32 v[8:9], v[8:9], v[216:217] op_sel_hi:[1,0] neg_lo:[0,1] neg_hi:[0,1]
	v_pk_add_f32 v[10:11], v[10:11], v[216:217] op_sel_hi:[1,0] neg_lo:[0,1] neg_hi:[0,1]
	v_pk_add_f32 v[12:13], v[12:13], v[216:217] op_sel_hi:[1,0] neg_lo:[0,1] neg_hi:[0,1]
	v_pk_add_f32 v[14:15], v[14:15], v[216:217] op_sel_hi:[1,0] neg_lo:[0,1] neg_hi:[0,1]
	v_pk_add_f32 v[16:17], v[16:17], v[216:217] op_sel_hi:[1,0] neg_lo:[0,1] neg_hi:[0,1]
	v_pk_mul_f32 v[76:77], v[2:3], v[2:3]
	v_pk_mul_f32 v[136:137], v[4:5], v[4:5]
	v_add_f32_e32 v133, v76, v77
	v_add_f32_e32 v133, v136, v133
	v_add_f32_e32 v133, v137, v133
	v_pk_mul_f32 v[76:77], v[6:7], v[6:7]
	v_pk_mul_f32 v[136:137], v[8:9], v[8:9]
	v_add_f32_e32 v133, v76, v133
	v_add_f32_e32 v133, v77, v133
	v_add_f32_e32 v133, v136, v133
	v_add_f32_e32 v133, v137, v133
	v_pk_mul_f32 v[76:77], v[10:11], v[10:11]
	v_pk_mul_f32 v[136:137], v[12:13], v[12:13]
	v_add_f32_e32 v133, v76, v133
	v_add_f32_e32 v133, v77, v133
	v_add_f32_e32 v133, v136, v133
	v_add_f32_e32 v133, v137, v133
	v_pk_mul_f32 v[76:77], v[14:15], v[14:15]
	v_pk_mul_f32 v[136:137], v[16:17], v[16:17]
	v_add_f32_e32 v133, v76, v133
	v_add_f32_e32 v133, v77, v133
	v_add_f32_e32 v133, v136, v133
	v_add_f32_e32 v133, v137, v133
	s_nop 1
	v_add_f32_dpp v133, v133, v133 quad_perm:[1,0,3,2] row_mask:0xf bank_mask:0xf bound_ctrl:1
	s_nop 1
	v_add_f32_dpp v133, v133, v133 quad_perm:[2,3,0,1] row_mask:0xf bank_mask:0xf bound_ctrl:1
	s_nop 1
	v_add_f32_dpp v133, v133, v133 row_half_mirror row_mask:0xf bank_mask:0xf bound_ctrl:1
	s_nop 1
	v_add_f32_dpp v133, v133, v133 row_mirror row_mask:0xf bank_mask:0xf bound_ctrl:1
	s_nop 1
	v_readlane_b32 s56, v133, 0
	v_readlane_b32 s57, v133, 16
	v_readlane_b32 s58, v133, 32
	v_readlane_b32 s59, v133, 48
	v_mov_b32_e32 v222, s57
	v_mov_b32_e32 v223, s59
	v_add_f32_e32 v222, s56, v222
	v_add_f32_e32 v223, s58, v223
	v_add_f32_e32 v133, v222, v223
	v_fmamk_f32 v133, v133, 0x3a800000, v215
	v_cmp_gt_f32_e32 vcc, s33, v133
	v_mul_f32_e32 v222, 0x4b800000, v133
	s_nop 0
	v_cndmask_b32_e32 v133, v133, v222, vcc
	v_rsq_f32_e32 v133, v133
	s_nop 0
	v_mul_f32_e32 v222, 0x45800000, v133
	v_cndmask_b32_e32 v220, v133, v222, vcc
	v_pk_mul_f32 v[2:3], v[2:3], v[220:221] op_sel_hi:[1,0]
	v_pk_mul_f32 v[4:5], v[4:5], v[220:221] op_sel_hi:[1,0]
	v_pk_mul_f32 v[6:7], v[6:7], v[220:221] op_sel_hi:[1,0]
	v_pk_mul_f32 v[8:9], v[8:9], v[220:221] op_sel_hi:[1,0]
	v_pk_mul_f32 v[10:11], v[10:11], v[220:221] op_sel_hi:[1,0]
	v_pk_mul_f32 v[12:13], v[12:13], v[220:221] op_sel_hi:[1,0]
	v_pk_mul_f32 v[14:15], v[14:15], v[220:221] op_sel_hi:[1,0]
	v_pk_mul_f32 v[16:17], v[16:17], v[220:221] op_sel_hi:[1,0]
	v_pk_fma_f32 v[2:3], v[184:185], v[2:3], v[200:201]
	v_pk_fma_f32 v[4:5], v[186:187], v[4:5], v[202:203]
	v_pk_fma_f32 v[6:7], v[188:189], v[6:7], v[204:205]
	v_pk_fma_f32 v[8:9], v[190:191], v[8:9], v[206:207]
	v_pk_fma_f32 v[10:11], v[192:193], v[10:11], v[226:227]
	v_pk_fma_f32 v[12:13], v[194:195], v[12:13], v[228:229]
	v_pk_fma_f32 v[14:15], v[196:197], v[14:15], v[230:231]
	v_pk_fma_f32 v[16:17], v[198:199], v[16:17], v[232:233]
	global_store_dwordx4 v212, v[2:5], s[42:43] offset:0
	global_store_dwordx4 v212, v[6:9], s[42:43] offset:1024
	global_store_dwordx4 v212, v[10:13], s[42:43] offset:2048
	global_store_dwordx4 v212, v[14:17], s[42:43] offset:3072
	v_cvt_pk_bf16_f32 v2, v2, v3
	v_cvt_pk_bf16_f32 v3, v4, v5
	v_cvt_pk_bf16_f32 v6, v6, v7
	v_cvt_pk_bf16_f32 v7, v8, v9
	v_cvt_pk_bf16_f32 v10, v10, v11
	v_cvt_pk_bf16_f32 v11, v12, v13
	v_cvt_pk_bf16_f32 v14, v14, v15
	v_cvt_pk_bf16_f32 v15, v16, v17
	global_store_dwordx2 v214, v[2:3], s[66:67] offset:0
	global_store_dwordx2 v214, v[6:7], s[66:67] offset:512
	global_store_dwordx2 v214, v[10:11], s[66:67] offset:1024
	global_store_dwordx2 v214, v[14:15], s[66:67] offset:1536
	s_waitcnt vmcnt(32)
	v_pk_add_f32 v[76:77], v[18:19], v[20:21]
	v_pk_add_f32 v[136:137], v[22:23], v[24:25]
	v_pk_add_f32 v[138:139], v[34:35], v[36:37]
	v_pk_add_f32 v[208:209], v[38:39], v[40:41]
	v_pk_add_f32 v[76:77], v[76:77], v[136:137]
	v_pk_add_f32 v[138:139], v[138:139], v[208:209]
	v_pk_add_f32 v[76:77], v[76:77], v[138:139]
	v_add_f32_e32 v131, v76, v77
	s_nop 1
	v_add_f32_dpp v131, v131, v131 quad_perm:[1,0,3,2] row_mask:0xf bank_mask:0xf bound_ctrl:1
	s_nop 1
	v_add_f32_dpp v131, v131, v131 quad_perm:[2,3,0,1] row_mask:0xf bank_mask:0xf bound_ctrl:1
	s_nop 1
	v_add_f32_dpp v131, v131, v131 row_half_mirror row_mask:0xf bank_mask:0xf bound_ctrl:1
	s_nop 1
	v_add_f32_dpp v131, v131, v131 row_mirror row_mask:0xf bank_mask:0xf bound_ctrl:1
	s_nop 1
	v_readlane_b32 s56, v131, 0
	v_readlane_b32 s57, v131, 16
	v_readlane_b32 s58, v131, 32
	v_readlane_b32 s59, v131, 48
	v_mov_b32_e32 v222, s57
	v_mov_b32_e32 v223, s59
	v_add_f32_e32 v222, s56, v222
	v_add_f32_e32 v223, s58, v223
	v_add_f32_e32 v131, v222, v223
	v_mul_f32_e32 v216, 0x3a800000, v131
	v_pk_add_f32 v[18:19], v[18:19], v[216:217] op_sel_hi:[1,0] neg_lo:[0,1] neg_hi:[0,1]
	v_pk_add_f32 v[20:21], v[20:21], v[216:217] op_sel_hi:[1,0] neg_lo:[0,1] neg_hi:[0,1]
	v_pk_add_f32 v[22:23], v[22:23], v[216:217] op_sel_hi:[1,0] neg_lo:[0,1] neg_hi:[0,1]
	v_pk_add_f32 v[24:25], v[24:25], v[216:217] op_sel_hi:[1,0] neg_lo:[0,1] neg_hi:[0,1]
	v_pk_add_f32 v[34:35], v[34:35], v[216:217] op_sel_hi:[1,0] neg_lo:[0,1] neg_hi:[0,1]
	v_pk_add_f32 v[36:37], v[36:37], v[216:217] op_sel_hi:[1,0] neg_lo:[0,1] neg_hi:[0,1]
	v_pk_add_f32 v[38:39], v[38:39], v[216:217] op_sel_hi:[1,0] neg_lo:[0,1] neg_hi:[0,1]
	v_pk_add_f32 v[40:41], v[40:41], v[216:217] op_sel_hi:[1,0] neg_lo:[0,1] neg_hi:[0,1]
	v_pk_mul_f32 v[76:77], v[18:19], v[18:19]
	v_pk_mul_f32 v[136:137], v[20:21], v[20:21]
	v_add_f32_e32 v133, v76, v77
	v_add_f32_e32 v133, v136, v133
	v_add_f32_e32 v133, v137, v133
	v_pk_mul_f32 v[76:77], v[22:23], v[22:23]
	v_pk_mul_f32 v[136:137], v[24:25], v[24:25]
	v_add_f32_e32 v133, v76, v133
	v_add_f32_e32 v133, v77, v133
	v_add_f32_e32 v133, v136, v133
	v_add_f32_e32 v133, v137, v133
	v_pk_mul_f32 v[76:77], v[34:35], v[34:35]
	v_pk_mul_f32 v[136:137], v[36:37], v[36:37]
	v_add_f32_e32 v133, v76, v133
	v_add_f32_e32 v133, v77, v133
	v_add_f32_e32 v133, v136, v133
	v_add_f32_e32 v133, v137, v133
	v_pk_mul_f32 v[76:77], v[38:39], v[38:39]
	v_pk_mul_f32 v[136:137], v[40:41], v[40:41]
	v_add_f32_e32 v133, v76, v133
	v_add_f32_e32 v133, v77, v133
	v_add_f32_e32 v133, v136, v133
	v_add_f32_e32 v133, v137, v133
	s_nop 1
	v_add_f32_dpp v133, v133, v133 quad_perm:[1,0,3,2] row_mask:0xf bank_mask:0xf bound_ctrl:1
	s_nop 1
	v_add_f32_dpp v133, v133, v133 quad_perm:[2,3,0,1] row_mask:0xf bank_mask:0xf bound_ctrl:1
	s_nop 1
	v_add_f32_dpp v133, v133, v133 row_half_mirror row_mask:0xf bank_mask:0xf bound_ctrl:1
	s_nop 1
	v_add_f32_dpp v133, v133, v133 row_mirror row_mask:0xf bank_mask:0xf bound_ctrl:1
	s_nop 1
	v_readlane_b32 s56, v133, 0
	v_readlane_b32 s57, v133, 16
	v_readlane_b32 s58, v133, 32
	v_readlane_b32 s59, v133, 48
	v_mov_b32_e32 v222, s57
	v_mov_b32_e32 v223, s59
	v_add_f32_e32 v222, s56, v222
	v_add_f32_e32 v223, s58, v223
	v_add_f32_e32 v133, v222, v223
	v_fmamk_f32 v133, v133, 0x3a800000, v215
	v_cmp_gt_f32_e32 vcc, s33, v133
	v_mul_f32_e32 v222, 0x4b800000, v133
	s_nop 0
	v_cndmask_b32_e32 v133, v133, v222, vcc
	v_rsq_f32_e32 v133, v133
	s_nop 0
	v_mul_f32_e32 v222, 0x45800000, v133
	v_cndmask_b32_e32 v220, v133, v222, vcc
	v_pk_mul_f32 v[18:19], v[18:19], v[220:221] op_sel_hi:[1,0]
	v_pk_mul_f32 v[20:21], v[20:21], v[220:221] op_sel_hi:[1,0]
	v_pk_mul_f32 v[22:23], v[22:23], v[220:221] op_sel_hi:[1,0]
	v_pk_mul_f32 v[24:25], v[24:25], v[220:221] op_sel_hi:[1,0]
	v_pk_mul_f32 v[34:35], v[34:35], v[220:221] op_sel_hi:[1,0]
	v_pk_mul_f32 v[36:37], v[36:37], v[220:221] op_sel_hi:[1,0]
	v_pk_mul_f32 v[38:39], v[38:39], v[220:221] op_sel_hi:[1,0]
	v_pk_mul_f32 v[40:41], v[40:41], v[220:221] op_sel_hi:[1,0]
	v_pk_fma_f32 v[18:19], v[184:185], v[18:19], v[200:201]
	v_pk_fma_f32 v[20:21], v[186:187], v[20:21], v[202:203]
	v_pk_fma_f32 v[22:23], v[188:189], v[22:23], v[204:205]
	v_pk_fma_f32 v[24:25], v[190:191], v[24:25], v[206:207]
	v_pk_fma_f32 v[34:35], v[192:193], v[34:35], v[226:227]
	v_pk_fma_f32 v[36:37], v[194:195], v[36:37], v[228:229]
	v_pk_fma_f32 v[38:39], v[196:197], v[38:39], v[230:231]
	v_pk_fma_f32 v[40:41], v[198:199], v[40:41], v[232:233]
	global_store_dwordx4 v212, v[18:21], s[44:45] offset:0
	global_store_dwordx4 v212, v[22:25], s[44:45] offset:1024
	global_store_dwordx4 v212, v[34:37], s[44:45] offset:2048
	global_store_dwordx4 v212, v[38:41], s[44:45] offset:3072
	v_cvt_pk_bf16_f32 v18, v18, v19
	v_cvt_pk_bf16_f32 v19, v20, v21
	v_cvt_pk_bf16_f32 v22, v22, v23
	v_cvt_pk_bf16_f32 v23, v24, v25
	v_cvt_pk_bf16_f32 v34, v34, v35
	v_cvt_pk_bf16_f32 v35, v36, v37
	v_cvt_pk_bf16_f32 v38, v38, v39
	v_cvt_pk_bf16_f32 v39, v40, v41
	global_store_dwordx2 v214, v[18:19], s[66:67] offset:2048
	global_store_dwordx2 v214, v[22:23], s[66:67] offset:2560
	global_store_dwordx2 v214, v[34:35], s[66:67] offset:3072
	global_store_dwordx2 v214, v[38:39], s[66:67] offset:3584
	s_waitcnt vmcnt(36)
	v_pk_add_f32 v[76:77], v[44:45], v[46:47]
	v_pk_add_f32 v[136:137], v[48:49], v[50:51]
	v_pk_add_f32 v[138:139], v[52:53], v[54:55]
	v_pk_add_f32 v[208:209], v[56:57], v[58:59]
	v_pk_add_f32 v[76:77], v[76:77], v[136:137]
	v_pk_add_f32 v[138:139], v[138:139], v[208:209]
	v_pk_add_f32 v[76:77], v[76:77], v[138:139]
	v_add_f32_e32 v131, v76, v77
	s_nop 1
	v_add_f32_dpp v131, v131, v131 quad_perm:[1,0,3,2] row_mask:0xf bank_mask:0xf bound_ctrl:1
	s_nop 1
	v_add_f32_dpp v131, v131, v131 quad_perm:[2,3,0,1] row_mask:0xf bank_mask:0xf bound_ctrl:1
	s_nop 1
	v_add_f32_dpp v131, v131, v131 row_half_mirror row_mask:0xf bank_mask:0xf bound_ctrl:1
	s_nop 1
	v_add_f32_dpp v131, v131, v131 row_mirror row_mask:0xf bank_mask:0xf bound_ctrl:1
	s_nop 1
	v_readlane_b32 s56, v131, 0
	v_readlane_b32 s57, v131, 16
	v_readlane_b32 s58, v131, 32
	v_readlane_b32 s59, v131, 48
	v_mov_b32_e32 v222, s57
	v_mov_b32_e32 v223, s59
	v_add_f32_e32 v222, s56, v222
	v_add_f32_e32 v223, s58, v223
	v_add_f32_e32 v131, v222, v223
	v_mul_f32_e32 v216, 0x3a800000, v131
	v_pk_add_f32 v[44:45], v[44:45], v[216:217] op_sel_hi:[1,0] neg_lo:[0,1] neg_hi:[0,1]
	v_pk_add_f32 v[46:47], v[46:47], v[216:217] op_sel_hi:[1,0] neg_lo:[0,1] neg_hi:[0,1]
	v_pk_add_f32 v[48:49], v[48:49], v[216:217] op_sel_hi:[1,0] neg_lo:[0,1] neg_hi:[0,1]
	v_pk_add_f32 v[50:51], v[50:51], v[216:217] op_sel_hi:[1,0] neg_lo:[0,1] neg_hi:[0,1]
	v_pk_add_f32 v[52:53], v[52:53], v[216:217] op_sel_hi:[1,0] neg_lo:[0,1] neg_hi:[0,1]
	v_pk_add_f32 v[54:55], v[54:55], v[216:217] op_sel_hi:[1,0] neg_lo:[0,1] neg_hi:[0,1]
	v_pk_add_f32 v[56:57], v[56:57], v[216:217] op_sel_hi:[1,0] neg_lo:[0,1] neg_hi:[0,1]
	v_pk_add_f32 v[58:59], v[58:59], v[216:217] op_sel_hi:[1,0] neg_lo:[0,1] neg_hi:[0,1]
	v_pk_mul_f32 v[76:77], v[44:45], v[44:45]
	v_pk_mul_f32 v[136:137], v[46:47], v[46:47]
	v_add_f32_e32 v133, v76, v77
	v_add_f32_e32 v133, v136, v133
	v_add_f32_e32 v133, v137, v133
	v_pk_mul_f32 v[76:77], v[48:49], v[48:49]
	v_pk_mul_f32 v[136:137], v[50:51], v[50:51]
	v_add_f32_e32 v133, v76, v133
	v_add_f32_e32 v133, v77, v133
	v_add_f32_e32 v133, v136, v133
	v_add_f32_e32 v133, v137, v133
	v_pk_mul_f32 v[76:77], v[52:53], v[52:53]
	v_pk_mul_f32 v[136:137], v[54:55], v[54:55]
	v_add_f32_e32 v133, v76, v133
	v_add_f32_e32 v133, v77, v133
	v_add_f32_e32 v133, v136, v133
	v_add_f32_e32 v133, v137, v133
	v_pk_mul_f32 v[76:77], v[56:57], v[56:57]
	v_pk_mul_f32 v[136:137], v[58:59], v[58:59]
	v_add_f32_e32 v133, v76, v133
	v_add_f32_e32 v133, v77, v133
	v_add_f32_e32 v133, v136, v133
	v_add_f32_e32 v133, v137, v133
	s_nop 1
	v_add_f32_dpp v133, v133, v133 quad_perm:[1,0,3,2] row_mask:0xf bank_mask:0xf bound_ctrl:1
	s_nop 1
	v_add_f32_dpp v133, v133, v133 quad_perm:[2,3,0,1] row_mask:0xf bank_mask:0xf bound_ctrl:1
	s_nop 1
	v_add_f32_dpp v133, v133, v133 row_half_mirror row_mask:0xf bank_mask:0xf bound_ctrl:1
	s_nop 1
	v_add_f32_dpp v133, v133, v133 row_mirror row_mask:0xf bank_mask:0xf bound_ctrl:1
	s_nop 1
	v_readlane_b32 s56, v133, 0
	v_readlane_b32 s57, v133, 16
	v_readlane_b32 s58, v133, 32
	v_readlane_b32 s59, v133, 48
	v_mov_b32_e32 v222, s57
	v_mov_b32_e32 v223, s59
	v_add_f32_e32 v222, s56, v222
	v_add_f32_e32 v223, s58, v223
	v_add_f32_e32 v133, v222, v223
	v_fmamk_f32 v133, v133, 0x3a800000, v215
	v_cmp_gt_f32_e32 vcc, s33, v133
	v_mul_f32_e32 v222, 0x4b800000, v133
	s_nop 0
	v_cndmask_b32_e32 v133, v133, v222, vcc
	v_rsq_f32_e32 v133, v133
	s_nop 0
	v_mul_f32_e32 v222, 0x45800000, v133
	v_cndmask_b32_e32 v220, v133, v222, vcc
	v_pk_mul_f32 v[44:45], v[44:45], v[220:221] op_sel_hi:[1,0]
	v_pk_mul_f32 v[46:47], v[46:47], v[220:221] op_sel_hi:[1,0]
	v_pk_mul_f32 v[48:49], v[48:49], v[220:221] op_sel_hi:[1,0]
	v_pk_mul_f32 v[50:51], v[50:51], v[220:221] op_sel_hi:[1,0]
	v_pk_mul_f32 v[52:53], v[52:53], v[220:221] op_sel_hi:[1,0]
	v_pk_mul_f32 v[54:55], v[54:55], v[220:221] op_sel_hi:[1,0]
	v_pk_mul_f32 v[56:57], v[56:57], v[220:221] op_sel_hi:[1,0]
	v_pk_mul_f32 v[58:59], v[58:59], v[220:221] op_sel_hi:[1,0]
	v_pk_fma_f32 v[44:45], v[184:185], v[44:45], v[200:201]
	v_pk_fma_f32 v[46:47], v[186:187], v[46:47], v[202:203]
	v_pk_fma_f32 v[48:49], v[188:189], v[48:49], v[204:205]
	v_pk_fma_f32 v[50:51], v[190:191], v[50:51], v[206:207]
	v_pk_fma_f32 v[52:53], v[192:193], v[52:53], v[226:227]
	v_pk_fma_f32 v[54:55], v[194:195], v[54:55], v[228:229]
	v_pk_fma_f32 v[56:57], v[196:197], v[56:57], v[230:231]
	v_pk_fma_f32 v[58:59], v[198:199], v[58:59], v[232:233]
	global_store_dwordx4 v212, v[44:47], s[46:47] offset:0
	global_store_dwordx4 v212, v[48:51], s[46:47] offset:1024
	global_store_dwordx4 v212, v[52:55], s[46:47] offset:2048
	global_store_dwordx4 v212, v[56:59], s[46:47] offset:3072
	v_cvt_pk_bf16_f32 v44, v44, v45
	v_cvt_pk_bf16_f32 v45, v46, v47
	v_cvt_pk_bf16_f32 v48, v48, v49
	v_cvt_pk_bf16_f32 v49, v50, v51
	v_cvt_pk_bf16_f32 v52, v52, v53
	v_cvt_pk_bf16_f32 v53, v54, v55
	v_cvt_pk_bf16_f32 v56, v56, v57
	v_cvt_pk_bf16_f32 v57, v58, v59
	global_store_dwordx2 v214, v[44:45], s[68:69] offset:0
	global_store_dwordx2 v214, v[48:49], s[68:69] offset:512
	global_store_dwordx2 v214, v[52:53], s[68:69] offset:1024
	global_store_dwordx2 v214, v[56:57], s[68:69] offset:1536
	s_waitcnt vmcnt(40)
	v_pk_add_f32 v[76:77], v[60:61], v[62:63]
	v_pk_add_f32 v[136:137], v[64:65], v[66:67]
	v_pk_add_f32 v[138:139], v[94:95], v[96:97]
	v_pk_add_f32 v[208:209], v[98:99], v[100:101]
	v_pk_add_f32 v[76:77], v[76:77], v[136:137]
	v_pk_add_f32 v[138:139], v[138:139], v[208:209]
	v_pk_add_f32 v[76:77], v[76:77], v[138:139]
	v_add_f32_e32 v131, v76, v77
	s_nop 1
	v_add_f32_dpp v131, v131, v131 quad_perm:[1,0,3,2] row_mask:0xf bank_mask:0xf bound_ctrl:1
	s_nop 1
	v_add_f32_dpp v131, v131, v131 quad_perm:[2,3,0,1] row_mask:0xf bank_mask:0xf bound_ctrl:1
	s_nop 1
	v_add_f32_dpp v131, v131, v131 row_half_mirror row_mask:0xf bank_mask:0xf bound_ctrl:1
	s_nop 1
	v_add_f32_dpp v131, v131, v131 row_mirror row_mask:0xf bank_mask:0xf bound_ctrl:1
	s_nop 1
	v_readlane_b32 s56, v131, 0
	v_readlane_b32 s57, v131, 16
	v_readlane_b32 s58, v131, 32
	v_readlane_b32 s59, v131, 48
	v_mov_b32_e32 v222, s57
	v_mov_b32_e32 v223, s59
	v_add_f32_e32 v222, s56, v222
	v_add_f32_e32 v223, s58, v223
	v_add_f32_e32 v131, v222, v223
	v_mul_f32_e32 v216, 0x3a800000, v131
	v_pk_add_f32 v[60:61], v[60:61], v[216:217] op_sel_hi:[1,0] neg_lo:[0,1] neg_hi:[0,1]
	v_pk_add_f32 v[62:63], v[62:63], v[216:217] op_sel_hi:[1,0] neg_lo:[0,1] neg_hi:[0,1]
	v_pk_add_f32 v[64:65], v[64:65], v[216:217] op_sel_hi:[1,0] neg_lo:[0,1] neg_hi:[0,1]
	v_pk_add_f32 v[66:67], v[66:67], v[216:217] op_sel_hi:[1,0] neg_lo:[0,1] neg_hi:[0,1]
	v_pk_add_f32 v[94:95], v[94:95], v[216:217] op_sel_hi:[1,0] neg_lo:[0,1] neg_hi:[0,1]
	v_pk_add_f32 v[96:97], v[96:97], v[216:217] op_sel_hi:[1,0] neg_lo:[0,1] neg_hi:[0,1]
	v_pk_add_f32 v[98:99], v[98:99], v[216:217] op_sel_hi:[1,0] neg_lo:[0,1] neg_hi:[0,1]
	v_pk_add_f32 v[100:101], v[100:101], v[216:217] op_sel_hi:[1,0] neg_lo:[0,1] neg_hi:[0,1]
	v_pk_mul_f32 v[76:77], v[60:61], v[60:61]
	v_pk_mul_f32 v[136:137], v[62:63], v[62:63]
	v_add_f32_e32 v133, v76, v77
	v_add_f32_e32 v133, v136, v133
	v_add_f32_e32 v133, v137, v133
	v_pk_mul_f32 v[76:77], v[64:65], v[64:65]
	v_pk_mul_f32 v[136:137], v[66:67], v[66:67]
	v_add_f32_e32 v133, v76, v133
	v_add_f32_e32 v133, v77, v133
	v_add_f32_e32 v133, v136, v133
	v_add_f32_e32 v133, v137, v133
	v_pk_mul_f32 v[76:77], v[94:95], v[94:95]
	v_pk_mul_f32 v[136:137], v[96:97], v[96:97]
	v_add_f32_e32 v133, v76, v133
	v_add_f32_e32 v133, v77, v133
	v_add_f32_e32 v133, v136, v133
	v_add_f32_e32 v133, v137, v133
	v_pk_mul_f32 v[76:77], v[98:99], v[98:99]
	v_pk_mul_f32 v[136:137], v[100:101], v[100:101]
	v_add_f32_e32 v133, v76, v133
	v_add_f32_e32 v133, v77, v133
	v_add_f32_e32 v133, v136, v133
	v_add_f32_e32 v133, v137, v133
	s_nop 1
	v_add_f32_dpp v133, v133, v133 quad_perm:[1,0,3,2] row_mask:0xf bank_mask:0xf bound_ctrl:1
	s_nop 1
	v_add_f32_dpp v133, v133, v133 quad_perm:[2,3,0,1] row_mask:0xf bank_mask:0xf bound_ctrl:1
	s_nop 1
	v_add_f32_dpp v133, v133, v133 row_half_mirror row_mask:0xf bank_mask:0xf bound_ctrl:1
	s_nop 1
	v_add_f32_dpp v133, v133, v133 row_mirror row_mask:0xf bank_mask:0xf bound_ctrl:1
	s_nop 1
	v_readlane_b32 s56, v133, 0
	v_readlane_b32 s57, v133, 16
	v_readlane_b32 s58, v133, 32
	v_readlane_b32 s59, v133, 48
	v_mov_b32_e32 v222, s57
	v_mov_b32_e32 v223, s59
	v_add_f32_e32 v222, s56, v222
	v_add_f32_e32 v223, s58, v223
	v_add_f32_e32 v133, v222, v223
	v_fmamk_f32 v133, v133, 0x3a800000, v215
	v_cmp_gt_f32_e32 vcc, s33, v133
	v_mul_f32_e32 v222, 0x4b800000, v133
	s_nop 0
	v_cndmask_b32_e32 v133, v133, v222, vcc
	v_rsq_f32_e32 v133, v133
	s_nop 0
	v_mul_f32_e32 v222, 0x45800000, v133
	v_cndmask_b32_e32 v220, v133, v222, vcc
	v_pk_mul_f32 v[60:61], v[60:61], v[220:221] op_sel_hi:[1,0]
	v_pk_mul_f32 v[62:63], v[62:63], v[220:221] op_sel_hi:[1,0]
	v_pk_mul_f32 v[64:65], v[64:65], v[220:221] op_sel_hi:[1,0]
	v_pk_mul_f32 v[66:67], v[66:67], v[220:221] op_sel_hi:[1,0]
	v_pk_mul_f32 v[94:95], v[94:95], v[220:221] op_sel_hi:[1,0]
	v_pk_mul_f32 v[96:97], v[96:97], v[220:221] op_sel_hi:[1,0]
	v_pk_mul_f32 v[98:99], v[98:99], v[220:221] op_sel_hi:[1,0]
	v_pk_mul_f32 v[100:101], v[100:101], v[220:221] op_sel_hi:[1,0]
	v_pk_fma_f32 v[60:61], v[184:185], v[60:61], v[200:201]
	v_pk_fma_f32 v[62:63], v[186:187], v[62:63], v[202:203]
	v_pk_fma_f32 v[64:65], v[188:189], v[64:65], v[204:205]
	v_pk_fma_f32 v[66:67], v[190:191], v[66:67], v[206:207]
	v_pk_fma_f32 v[94:95], v[192:193], v[94:95], v[226:227]
	v_pk_fma_f32 v[96:97], v[194:195], v[96:97], v[228:229]
	v_pk_fma_f32 v[98:99], v[196:197], v[98:99], v[230:231]
	v_pk_fma_f32 v[100:101], v[198:199], v[100:101], v[232:233]
	global_store_dwordx4 v212, v[60:63], s[48:49] offset:0
	global_store_dwordx4 v212, v[64:67], s[48:49] offset:1024
	global_store_dwordx4 v212, v[94:97], s[48:49] offset:2048
	global_store_dwordx4 v212, v[98:101], s[48:49] offset:3072
	v_cvt_pk_bf16_f32 v60, v60, v61
	v_cvt_pk_bf16_f32 v61, v62, v63
	v_cvt_pk_bf16_f32 v64, v64, v65
	v_cvt_pk_bf16_f32 v65, v66, v67
	v_cvt_pk_bf16_f32 v94, v94, v95
	v_cvt_pk_bf16_f32 v95, v96, v97
	v_cvt_pk_bf16_f32 v98, v98, v99
	v_cvt_pk_bf16_f32 v99, v100, v101
	global_store_dwordx2 v214, v[60:61], s[68:69] offset:2048
	global_store_dwordx2 v214, v[64:65], s[68:69] offset:2560
	global_store_dwordx2 v214, v[94:95], s[68:69] offset:3072
	global_store_dwordx2 v214, v[98:99], s[68:69] offset:3584
	s_waitcnt vmcnt(44)
	v_pk_add_f32 v[76:77], v[102:103], v[104:105]
	v_pk_add_f32 v[136:137], v[106:107], v[108:109]
	v_pk_add_f32 v[138:139], v[110:111], v[112:113]
	v_pk_add_f32 v[208:209], v[114:115], v[116:117]
	v_pk_add_f32 v[76:77], v[76:77], v[136:137]
	v_pk_add_f32 v[138:139], v[138:139], v[208:209]
	v_pk_add_f32 v[76:77], v[76:77], v[138:139]
	v_add_f32_e32 v131, v76, v77
	s_nop 1
	v_add_f32_dpp v131, v131, v131 quad_perm:[1,0,3,2] row_mask:0xf bank_mask:0xf bound_ctrl:1
	s_nop 1
	v_add_f32_dpp v131, v131, v131 quad_perm:[2,3,0,1] row_mask:0xf bank_mask:0xf bound_ctrl:1
	s_nop 1
	v_add_f32_dpp v131, v131, v131 row_half_mirror row_mask:0xf bank_mask:0xf bound_ctrl:1
	s_nop 1
	v_add_f32_dpp v131, v131, v131 row_mirror row_mask:0xf bank_mask:0xf bound_ctrl:1
	s_nop 1
	v_readlane_b32 s56, v131, 0
	v_readlane_b32 s57, v131, 16
	v_readlane_b32 s58, v131, 32
	v_readlane_b32 s59, v131, 48
	v_mov_b32_e32 v222, s57
	v_mov_b32_e32 v223, s59
	v_add_f32_e32 v222, s56, v222
	v_add_f32_e32 v223, s58, v223
	v_add_f32_e32 v131, v222, v223
	v_mul_f32_e32 v216, 0x3a800000, v131
	v_pk_add_f32 v[102:103], v[102:103], v[216:217] op_sel_hi:[1,0] neg_lo:[0,1] neg_hi:[0,1]
	v_pk_add_f32 v[104:105], v[104:105], v[216:217] op_sel_hi:[1,0] neg_lo:[0,1] neg_hi:[0,1]
	v_pk_add_f32 v[106:107], v[106:107], v[216:217] op_sel_hi:[1,0] neg_lo:[0,1] neg_hi:[0,1]
	v_pk_add_f32 v[108:109], v[108:109], v[216:217] op_sel_hi:[1,0] neg_lo:[0,1] neg_hi:[0,1]
	v_pk_add_f32 v[110:111], v[110:111], v[216:217] op_sel_hi:[1,0] neg_lo:[0,1] neg_hi:[0,1]
	v_pk_add_f32 v[112:113], v[112:113], v[216:217] op_sel_hi:[1,0] neg_lo:[0,1] neg_hi:[0,1]
	v_pk_add_f32 v[114:115], v[114:115], v[216:217] op_sel_hi:[1,0] neg_lo:[0,1] neg_hi:[0,1]
	v_pk_add_f32 v[116:117], v[116:117], v[216:217] op_sel_hi:[1,0] neg_lo:[0,1] neg_hi:[0,1]
	v_pk_mul_f32 v[76:77], v[102:103], v[102:103]
	v_pk_mul_f32 v[136:137], v[104:105], v[104:105]
	v_add_f32_e32 v133, v76, v77
	v_add_f32_e32 v133, v136, v133
	v_add_f32_e32 v133, v137, v133
	v_pk_mul_f32 v[76:77], v[106:107], v[106:107]
	v_pk_mul_f32 v[136:137], v[108:109], v[108:109]
	v_add_f32_e32 v133, v76, v133
	v_add_f32_e32 v133, v77, v133
	v_add_f32_e32 v133, v136, v133
	v_add_f32_e32 v133, v137, v133
	v_pk_mul_f32 v[76:77], v[110:111], v[110:111]
	v_pk_mul_f32 v[136:137], v[112:113], v[112:113]
	v_add_f32_e32 v133, v76, v133
	v_add_f32_e32 v133, v77, v133
	v_add_f32_e32 v133, v136, v133
	v_add_f32_e32 v133, v137, v133
	v_pk_mul_f32 v[76:77], v[114:115], v[114:115]
	v_pk_mul_f32 v[136:137], v[116:117], v[116:117]
	v_add_f32_e32 v133, v76, v133
	v_add_f32_e32 v133, v77, v133
	v_add_f32_e32 v133, v136, v133
	v_add_f32_e32 v133, v137, v133
	s_nop 1
	v_add_f32_dpp v133, v133, v133 quad_perm:[1,0,3,2] row_mask:0xf bank_mask:0xf bound_ctrl:1
	s_nop 1
	v_add_f32_dpp v133, v133, v133 quad_perm:[2,3,0,1] row_mask:0xf bank_mask:0xf bound_ctrl:1
	s_nop 1
	v_add_f32_dpp v133, v133, v133 row_half_mirror row_mask:0xf bank_mask:0xf bound_ctrl:1
	s_nop 1
	v_add_f32_dpp v133, v133, v133 row_mirror row_mask:0xf bank_mask:0xf bound_ctrl:1
	s_nop 1
	v_readlane_b32 s56, v133, 0
	v_readlane_b32 s57, v133, 16
	v_readlane_b32 s58, v133, 32
	v_readlane_b32 s59, v133, 48
	v_mov_b32_e32 v222, s57
	v_mov_b32_e32 v223, s59
	v_add_f32_e32 v222, s56, v222
	v_add_f32_e32 v223, s58, v223
	v_add_f32_e32 v133, v222, v223
	v_fmamk_f32 v133, v133, 0x3a800000, v215
	v_cmp_gt_f32_e32 vcc, s33, v133
	v_mul_f32_e32 v222, 0x4b800000, v133
	s_nop 0
	v_cndmask_b32_e32 v133, v133, v222, vcc
	v_rsq_f32_e32 v133, v133
	s_nop 0
	v_mul_f32_e32 v222, 0x45800000, v133
	v_cndmask_b32_e32 v220, v133, v222, vcc
	v_pk_mul_f32 v[102:103], v[102:103], v[220:221] op_sel_hi:[1,0]
	v_pk_mul_f32 v[104:105], v[104:105], v[220:221] op_sel_hi:[1,0]
	v_pk_mul_f32 v[106:107], v[106:107], v[220:221] op_sel_hi:[1,0]
	v_pk_mul_f32 v[108:109], v[108:109], v[220:221] op_sel_hi:[1,0]
	v_pk_mul_f32 v[110:111], v[110:111], v[220:221] op_sel_hi:[1,0]
	v_pk_mul_f32 v[112:113], v[112:113], v[220:221] op_sel_hi:[1,0]
	v_pk_mul_f32 v[114:115], v[114:115], v[220:221] op_sel_hi:[1,0]
	v_pk_mul_f32 v[116:117], v[116:117], v[220:221] op_sel_hi:[1,0]
	v_pk_fma_f32 v[102:103], v[184:185], v[102:103], v[200:201]
	v_pk_fma_f32 v[104:105], v[186:187], v[104:105], v[202:203]
	v_pk_fma_f32 v[106:107], v[188:189], v[106:107], v[204:205]
	v_pk_fma_f32 v[108:109], v[190:191], v[108:109], v[206:207]
	v_pk_fma_f32 v[110:111], v[192:193], v[110:111], v[226:227]
	v_pk_fma_f32 v[112:113], v[194:195], v[112:113], v[228:229]
	v_pk_fma_f32 v[114:115], v[196:197], v[114:115], v[230:231]
	v_pk_fma_f32 v[116:117], v[198:199], v[116:117], v[232:233]
	global_store_dwordx4 v212, v[102:105], s[50:51] offset:0
	global_store_dwordx4 v212, v[106:109], s[50:51] offset:1024
	global_store_dwordx4 v212, v[110:113], s[50:51] offset:2048
	global_store_dwordx4 v212, v[114:117], s[50:51] offset:3072
	v_cvt_pk_bf16_f32 v102, v102, v103
	v_cvt_pk_bf16_f32 v103, v104, v105
	v_cvt_pk_bf16_f32 v106, v106, v107
	v_cvt_pk_bf16_f32 v107, v108, v109
	v_cvt_pk_bf16_f32 v110, v110, v111
	v_cvt_pk_bf16_f32 v111, v112, v113
	v_cvt_pk_bf16_f32 v114, v114, v115
	v_cvt_pk_bf16_f32 v115, v116, v117
	global_store_dwordx2 v214, v[102:103], s[70:71] offset:0
	global_store_dwordx2 v214, v[106:107], s[70:71] offset:512
	global_store_dwordx2 v214, v[110:111], s[70:71] offset:1024
	global_store_dwordx2 v214, v[114:115], s[70:71] offset:1536
	s_waitcnt vmcnt(48)
	v_pk_add_f32 v[76:77], v[118:119], v[120:121]
	v_pk_add_f32 v[136:137], v[122:123], v[124:125]
	v_pk_add_f32 v[138:139], v[144:145], v[146:147]
	v_pk_add_f32 v[208:209], v[148:149], v[150:151]
	v_pk_add_f32 v[76:77], v[76:77], v[136:137]
	v_pk_add_f32 v[138:139], v[138:139], v[208:209]
	v_pk_add_f32 v[76:77], v[76:77], v[138:139]
	v_add_f32_e32 v131, v76, v77
	s_nop 1
	v_add_f32_dpp v131, v131, v131 quad_perm:[1,0,3,2] row_mask:0xf bank_mask:0xf bound_ctrl:1
	s_nop 1
	v_add_f32_dpp v131, v131, v131 quad_perm:[2,3,0,1] row_mask:0xf bank_mask:0xf bound_ctrl:1
	s_nop 1
	v_add_f32_dpp v131, v131, v131 row_half_mirror row_mask:0xf bank_mask:0xf bound_ctrl:1
	s_nop 1
	v_add_f32_dpp v131, v131, v131 row_mirror row_mask:0xf bank_mask:0xf bound_ctrl:1
	s_nop 1
	v_readlane_b32 s56, v131, 0
	v_readlane_b32 s57, v131, 16
	v_readlane_b32 s58, v131, 32
	v_readlane_b32 s59, v131, 48
	v_mov_b32_e32 v222, s57
	v_mov_b32_e32 v223, s59
	v_add_f32_e32 v222, s56, v222
	v_add_f32_e32 v223, s58, v223
	v_add_f32_e32 v131, v222, v223
	v_mul_f32_e32 v216, 0x3a800000, v131
	v_pk_add_f32 v[118:119], v[118:119], v[216:217] op_sel_hi:[1,0] neg_lo:[0,1] neg_hi:[0,1]
	v_pk_add_f32 v[120:121], v[120:121], v[216:217] op_sel_hi:[1,0] neg_lo:[0,1] neg_hi:[0,1]
	v_pk_add_f32 v[122:123], v[122:123], v[216:217] op_sel_hi:[1,0] neg_lo:[0,1] neg_hi:[0,1]
	v_pk_add_f32 v[124:125], v[124:125], v[216:217] op_sel_hi:[1,0] neg_lo:[0,1] neg_hi:[0,1]
	v_pk_add_f32 v[144:145], v[144:145], v[216:217] op_sel_hi:[1,0] neg_lo:[0,1] neg_hi:[0,1]
	v_pk_add_f32 v[146:147], v[146:147], v[216:217] op_sel_hi:[1,0] neg_lo:[0,1] neg_hi:[0,1]
	v_pk_add_f32 v[148:149], v[148:149], v[216:217] op_sel_hi:[1,0] neg_lo:[0,1] neg_hi:[0,1]
	v_pk_add_f32 v[150:151], v[150:151], v[216:217] op_sel_hi:[1,0] neg_lo:[0,1] neg_hi:[0,1]
	v_pk_mul_f32 v[76:77], v[118:119], v[118:119]
	v_pk_mul_f32 v[136:137], v[120:121], v[120:121]
	v_add_f32_e32 v133, v76, v77
	v_add_f32_e32 v133, v136, v133
	v_add_f32_e32 v133, v137, v133
	v_pk_mul_f32 v[76:77], v[122:123], v[122:123]
	v_pk_mul_f32 v[136:137], v[124:125], v[124:125]
	v_add_f32_e32 v133, v76, v133
	v_add_f32_e32 v133, v77, v133
	v_add_f32_e32 v133, v136, v133
	v_add_f32_e32 v133, v137, v133
	v_pk_mul_f32 v[76:77], v[144:145], v[144:145]
	v_pk_mul_f32 v[136:137], v[146:147], v[146:147]
	v_add_f32_e32 v133, v76, v133
	v_add_f32_e32 v133, v77, v133
	v_add_f32_e32 v133, v136, v133
	v_add_f32_e32 v133, v137, v133
	v_pk_mul_f32 v[76:77], v[148:149], v[148:149]
	v_pk_mul_f32 v[136:137], v[150:151], v[150:151]
	v_add_f32_e32 v133, v76, v133
	v_add_f32_e32 v133, v77, v133
	v_add_f32_e32 v133, v136, v133
	v_add_f32_e32 v133, v137, v133
	s_nop 1
	v_add_f32_dpp v133, v133, v133 quad_perm:[1,0,3,2] row_mask:0xf bank_mask:0xf bound_ctrl:1
	s_nop 1
	v_add_f32_dpp v133, v133, v133 quad_perm:[2,3,0,1] row_mask:0xf bank_mask:0xf bound_ctrl:1
	s_nop 1
	v_add_f32_dpp v133, v133, v133 row_half_mirror row_mask:0xf bank_mask:0xf bound_ctrl:1
	s_nop 1
	v_add_f32_dpp v133, v133, v133 row_mirror row_mask:0xf bank_mask:0xf bound_ctrl:1
	s_nop 1
	v_readlane_b32 s56, v133, 0
	v_readlane_b32 s57, v133, 16
	v_readlane_b32 s58, v133, 32
	v_readlane_b32 s59, v133, 48
	v_mov_b32_e32 v222, s57
	v_mov_b32_e32 v223, s59
	v_add_f32_e32 v222, s56, v222
	v_add_f32_e32 v223, s58, v223
	v_add_f32_e32 v133, v222, v223
	v_fmamk_f32 v133, v133, 0x3a800000, v215
	v_cmp_gt_f32_e32 vcc, s33, v133
	v_mul_f32_e32 v222, 0x4b800000, v133
	s_nop 0
	v_cndmask_b32_e32 v133, v133, v222, vcc
	v_rsq_f32_e32 v133, v133
	s_nop 0
	v_mul_f32_e32 v222, 0x45800000, v133
	v_cndmask_b32_e32 v220, v133, v222, vcc
	v_pk_mul_f32 v[118:119], v[118:119], v[220:221] op_sel_hi:[1,0]
	v_pk_mul_f32 v[120:121], v[120:121], v[220:221] op_sel_hi:[1,0]
	v_pk_mul_f32 v[122:123], v[122:123], v[220:221] op_sel_hi:[1,0]
	v_pk_mul_f32 v[124:125], v[124:125], v[220:221] op_sel_hi:[1,0]
	v_pk_mul_f32 v[144:145], v[144:145], v[220:221] op_sel_hi:[1,0]
	v_pk_mul_f32 v[146:147], v[146:147], v[220:221] op_sel_hi:[1,0]
	v_pk_mul_f32 v[148:149], v[148:149], v[220:221] op_sel_hi:[1,0]
	v_pk_mul_f32 v[150:151], v[150:151], v[220:221] op_sel_hi:[1,0]
	v_pk_fma_f32 v[118:119], v[184:185], v[118:119], v[200:201]
	v_pk_fma_f32 v[120:121], v[186:187], v[120:121], v[202:203]
	v_pk_fma_f32 v[122:123], v[188:189], v[122:123], v[204:205]
	v_pk_fma_f32 v[124:125], v[190:191], v[124:125], v[206:207]
	v_pk_fma_f32 v[144:145], v[192:193], v[144:145], v[226:227]
	v_pk_fma_f32 v[146:147], v[194:195], v[146:147], v[228:229]
	v_pk_fma_f32 v[148:149], v[196:197], v[148:149], v[230:231]
	v_pk_fma_f32 v[150:151], v[198:199], v[150:151], v[232:233]
	global_store_dwordx4 v212, v[118:121], s[52:53] offset:0
	global_store_dwordx4 v212, v[122:125], s[52:53] offset:1024
	global_store_dwordx4 v212, v[144:147], s[52:53] offset:2048
	global_store_dwordx4 v212, v[148:151], s[52:53] offset:3072
	v_cvt_pk_bf16_f32 v118, v118, v119
	v_cvt_pk_bf16_f32 v119, v120, v121
	v_cvt_pk_bf16_f32 v122, v122, v123
	v_cvt_pk_bf16_f32 v123, v124, v125
	v_cvt_pk_bf16_f32 v144, v144, v145
	v_cvt_pk_bf16_f32 v145, v146, v147
	v_cvt_pk_bf16_f32 v148, v148, v149
	v_cvt_pk_bf16_f32 v149, v150, v151
	global_store_dwordx2 v214, v[118:119], s[70:71] offset:2048
	global_store_dwordx2 v214, v[122:123], s[70:71] offset:2560
	global_store_dwordx2 v214, v[144:145], s[70:71] offset:3072
	global_store_dwordx2 v214, v[148:149], s[70:71] offset:3584
	s_waitcnt vmcnt(52)
	v_pk_add_f32 v[76:77], v[152:153], v[154:155]
	v_pk_add_f32 v[136:137], v[156:157], v[158:159]
	v_pk_add_f32 v[138:139], v[160:161], v[162:163]
	v_pk_add_f32 v[208:209], v[164:165], v[166:167]
	v_pk_add_f32 v[76:77], v[76:77], v[136:137]
	v_pk_add_f32 v[138:139], v[138:139], v[208:209]
	v_pk_add_f32 v[76:77], v[76:77], v[138:139]
	v_add_f32_e32 v131, v76, v77
	s_nop 1
	v_add_f32_dpp v131, v131, v131 quad_perm:[1,0,3,2] row_mask:0xf bank_mask:0xf bound_ctrl:1
	s_nop 1
	v_add_f32_dpp v131, v131, v131 quad_perm:[2,3,0,1] row_mask:0xf bank_mask:0xf bound_ctrl:1
	s_nop 1
	v_add_f32_dpp v131, v131, v131 row_half_mirror row_mask:0xf bank_mask:0xf bound_ctrl:1
	s_nop 1
	v_add_f32_dpp v131, v131, v131 row_mirror row_mask:0xf bank_mask:0xf bound_ctrl:1
	s_nop 1
	v_readlane_b32 s56, v131, 0
	v_readlane_b32 s57, v131, 16
	v_readlane_b32 s58, v131, 32
	v_readlane_b32 s59, v131, 48
	v_mov_b32_e32 v222, s57
	v_mov_b32_e32 v223, s59
	v_add_f32_e32 v222, s56, v222
	v_add_f32_e32 v223, s58, v223
	v_add_f32_e32 v131, v222, v223
	v_mul_f32_e32 v216, 0x3a800000, v131
	v_pk_add_f32 v[152:153], v[152:153], v[216:217] op_sel_hi:[1,0] neg_lo:[0,1] neg_hi:[0,1]
	v_pk_add_f32 v[154:155], v[154:155], v[216:217] op_sel_hi:[1,0] neg_lo:[0,1] neg_hi:[0,1]
	v_pk_add_f32 v[156:157], v[156:157], v[216:217] op_sel_hi:[1,0] neg_lo:[0,1] neg_hi:[0,1]
	v_pk_add_f32 v[158:159], v[158:159], v[216:217] op_sel_hi:[1,0] neg_lo:[0,1] neg_hi:[0,1]
	v_pk_add_f32 v[160:161], v[160:161], v[216:217] op_sel_hi:[1,0] neg_lo:[0,1] neg_hi:[0,1]
	v_pk_add_f32 v[162:163], v[162:163], v[216:217] op_sel_hi:[1,0] neg_lo:[0,1] neg_hi:[0,1]
	v_pk_add_f32 v[164:165], v[164:165], v[216:217] op_sel_hi:[1,0] neg_lo:[0,1] neg_hi:[0,1]
	v_pk_add_f32 v[166:167], v[166:167], v[216:217] op_sel_hi:[1,0] neg_lo:[0,1] neg_hi:[0,1]
	v_pk_mul_f32 v[76:77], v[152:153], v[152:153]
	v_pk_mul_f32 v[136:137], v[154:155], v[154:155]
	v_add_f32_e32 v133, v76, v77
	v_add_f32_e32 v133, v136, v133
	v_add_f32_e32 v133, v137, v133
	v_pk_mul_f32 v[76:77], v[156:157], v[156:157]
	v_pk_mul_f32 v[136:137], v[158:159], v[158:159]
	v_add_f32_e32 v133, v76, v133
	v_add_f32_e32 v133, v77, v133
	v_add_f32_e32 v133, v136, v133
	v_add_f32_e32 v133, v137, v133
	v_pk_mul_f32 v[76:77], v[160:161], v[160:161]
	v_pk_mul_f32 v[136:137], v[162:163], v[162:163]
	v_add_f32_e32 v133, v76, v133
	v_add_f32_e32 v133, v77, v133
	v_add_f32_e32 v133, v136, v133
	v_add_f32_e32 v133, v137, v133
	v_pk_mul_f32 v[76:77], v[164:165], v[164:165]
	v_pk_mul_f32 v[136:137], v[166:167], v[166:167]
	v_add_f32_e32 v133, v76, v133
	v_add_f32_e32 v133, v77, v133
	v_add_f32_e32 v133, v136, v133
	v_add_f32_e32 v133, v137, v133
	s_nop 1
	v_add_f32_dpp v133, v133, v133 quad_perm:[1,0,3,2] row_mask:0xf bank_mask:0xf bound_ctrl:1
	s_nop 1
	v_add_f32_dpp v133, v133, v133 quad_perm:[2,3,0,1] row_mask:0xf bank_mask:0xf bound_ctrl:1
	s_nop 1
	v_add_f32_dpp v133, v133, v133 row_half_mirror row_mask:0xf bank_mask:0xf bound_ctrl:1
	s_nop 1
	v_add_f32_dpp v133, v133, v133 row_mirror row_mask:0xf bank_mask:0xf bound_ctrl:1
	s_nop 1
	v_readlane_b32 s56, v133, 0
	v_readlane_b32 s57, v133, 16
	v_readlane_b32 s58, v133, 32
	v_readlane_b32 s59, v133, 48
	v_mov_b32_e32 v222, s57
	v_mov_b32_e32 v223, s59
	v_add_f32_e32 v222, s56, v222
	v_add_f32_e32 v223, s58, v223
	v_add_f32_e32 v133, v222, v223
	v_fmamk_f32 v133, v133, 0x3a800000, v215
	v_cmp_gt_f32_e32 vcc, s33, v133
	v_mul_f32_e32 v222, 0x4b800000, v133
	s_nop 0
	v_cndmask_b32_e32 v133, v133, v222, vcc
	v_rsq_f32_e32 v133, v133
	s_nop 0
	v_mul_f32_e32 v222, 0x45800000, v133
	v_cndmask_b32_e32 v220, v133, v222, vcc
	v_pk_mul_f32 v[152:153], v[152:153], v[220:221] op_sel_hi:[1,0]
	v_pk_mul_f32 v[154:155], v[154:155], v[220:221] op_sel_hi:[1,0]
	v_pk_mul_f32 v[156:157], v[156:157], v[220:221] op_sel_hi:[1,0]
	v_pk_mul_f32 v[158:159], v[158:159], v[220:221] op_sel_hi:[1,0]
	v_pk_mul_f32 v[160:161], v[160:161], v[220:221] op_sel_hi:[1,0]
	v_pk_mul_f32 v[162:163], v[162:163], v[220:221] op_sel_hi:[1,0]
	v_pk_mul_f32 v[164:165], v[164:165], v[220:221] op_sel_hi:[1,0]
	v_pk_mul_f32 v[166:167], v[166:167], v[220:221] op_sel_hi:[1,0]
	v_pk_fma_f32 v[152:153], v[184:185], v[152:153], v[200:201]
	v_pk_fma_f32 v[154:155], v[186:187], v[154:155], v[202:203]
	v_pk_fma_f32 v[156:157], v[188:189], v[156:157], v[204:205]
	v_pk_fma_f32 v[158:159], v[190:191], v[158:159], v[206:207]
	v_pk_fma_f32 v[160:161], v[192:193], v[160:161], v[226:227]
	v_pk_fma_f32 v[162:163], v[194:195], v[162:163], v[228:229]
	v_pk_fma_f32 v[164:165], v[196:197], v[164:165], v[230:231]
	v_pk_fma_f32 v[166:167], v[198:199], v[166:167], v[232:233]
	global_store_dwordx4 v212, v[152:155], s[62:63] offset:0
	global_store_dwordx4 v212, v[156:159], s[62:63] offset:1024
	global_store_dwordx4 v212, v[160:163], s[62:63] offset:2048
	global_store_dwordx4 v212, v[164:167], s[62:63] offset:3072
	v_cvt_pk_bf16_f32 v152, v152, v153
	v_cvt_pk_bf16_f32 v153, v154, v155
	v_cvt_pk_bf16_f32 v156, v156, v157
	v_cvt_pk_bf16_f32 v157, v158, v159
	v_cvt_pk_bf16_f32 v160, v160, v161
	v_cvt_pk_bf16_f32 v161, v162, v163
	v_cvt_pk_bf16_f32 v164, v164, v165
	v_cvt_pk_bf16_f32 v165, v166, v167
	global_store_dwordx2 v214, v[152:153], s[72:73] offset:0
	global_store_dwordx2 v214, v[156:157], s[72:73] offset:512
	global_store_dwordx2 v214, v[160:161], s[72:73] offset:1024
	global_store_dwordx2 v214, v[164:165], s[72:73] offset:1536
	s_waitcnt vmcnt(56)
	v_pk_add_f32 v[76:77], v[168:169], v[170:171]
	v_pk_add_f32 v[136:137], v[172:173], v[174:175]
	v_pk_add_f32 v[138:139], v[176:177], v[178:179]
	v_pk_add_f32 v[208:209], v[180:181], v[182:183]
	v_pk_add_f32 v[76:77], v[76:77], v[136:137]
	v_pk_add_f32 v[138:139], v[138:139], v[208:209]
	v_pk_add_f32 v[76:77], v[76:77], v[138:139]
	v_add_f32_e32 v131, v76, v77
	s_nop 1
	v_add_f32_dpp v131, v131, v131 quad_perm:[1,0,3,2] row_mask:0xf bank_mask:0xf bound_ctrl:1
	s_nop 1
	v_add_f32_dpp v131, v131, v131 quad_perm:[2,3,0,1] row_mask:0xf bank_mask:0xf bound_ctrl:1
	s_nop 1
	v_add_f32_dpp v131, v131, v131 row_half_mirror row_mask:0xf bank_mask:0xf bound_ctrl:1
	s_nop 1
	v_add_f32_dpp v131, v131, v131 row_mirror row_mask:0xf bank_mask:0xf bound_ctrl:1
	s_nop 1
	v_readlane_b32 s56, v131, 0
	v_readlane_b32 s57, v131, 16
	v_readlane_b32 s58, v131, 32
	v_readlane_b32 s59, v131, 48
	v_mov_b32_e32 v222, s57
	v_mov_b32_e32 v223, s59
	v_add_f32_e32 v222, s56, v222
	v_add_f32_e32 v223, s58, v223
	v_add_f32_e32 v131, v222, v223
	v_mul_f32_e32 v216, 0x3a800000, v131
	v_pk_add_f32 v[168:169], v[168:169], v[216:217] op_sel_hi:[1,0] neg_lo:[0,1] neg_hi:[0,1]
	v_pk_add_f32 v[170:171], v[170:171], v[216:217] op_sel_hi:[1,0] neg_lo:[0,1] neg_hi:[0,1]
	v_pk_add_f32 v[172:173], v[172:173], v[216:217] op_sel_hi:[1,0] neg_lo:[0,1] neg_hi:[0,1]
	v_pk_add_f32 v[174:175], v[174:175], v[216:217] op_sel_hi:[1,0] neg_lo:[0,1] neg_hi:[0,1]
	v_pk_add_f32 v[176:177], v[176:177], v[216:217] op_sel_hi:[1,0] neg_lo:[0,1] neg_hi:[0,1]
	v_pk_add_f32 v[178:179], v[178:179], v[216:217] op_sel_hi:[1,0] neg_lo:[0,1] neg_hi:[0,1]
	v_pk_add_f32 v[180:181], v[180:181], v[216:217] op_sel_hi:[1,0] neg_lo:[0,1] neg_hi:[0,1]
	v_pk_add_f32 v[182:183], v[182:183], v[216:217] op_sel_hi:[1,0] neg_lo:[0,1] neg_hi:[0,1]
	v_pk_mul_f32 v[76:77], v[168:169], v[168:169]
	v_pk_mul_f32 v[136:137], v[170:171], v[170:171]
	v_add_f32_e32 v133, v76, v77
	v_add_f32_e32 v133, v136, v133
	v_add_f32_e32 v133, v137, v133
	v_pk_mul_f32 v[76:77], v[172:173], v[172:173]
	v_pk_mul_f32 v[136:137], v[174:175], v[174:175]
	v_add_f32_e32 v133, v76, v133
	v_add_f32_e32 v133, v77, v133
	v_add_f32_e32 v133, v136, v133
	v_add_f32_e32 v133, v137, v133
	v_pk_mul_f32 v[76:77], v[176:177], v[176:177]
	v_pk_mul_f32 v[136:137], v[178:179], v[178:179]
	v_add_f32_e32 v133, v76, v133
	v_add_f32_e32 v133, v77, v133
	v_add_f32_e32 v133, v136, v133
	v_add_f32_e32 v133, v137, v133
	v_pk_mul_f32 v[76:77], v[180:181], v[180:181]
	v_pk_mul_f32 v[136:137], v[182:183], v[182:183]
	v_add_f32_e32 v133, v76, v133
	v_add_f32_e32 v133, v77, v133
	v_add_f32_e32 v133, v136, v133
	v_add_f32_e32 v133, v137, v133
	s_nop 1
	v_add_f32_dpp v133, v133, v133 quad_perm:[1,0,3,2] row_mask:0xf bank_mask:0xf bound_ctrl:1
	s_nop 1
	v_add_f32_dpp v133, v133, v133 quad_perm:[2,3,0,1] row_mask:0xf bank_mask:0xf bound_ctrl:1
	s_nop 1
	v_add_f32_dpp v133, v133, v133 row_half_mirror row_mask:0xf bank_mask:0xf bound_ctrl:1
	s_nop 1
	v_add_f32_dpp v133, v133, v133 row_mirror row_mask:0xf bank_mask:0xf bound_ctrl:1
	s_nop 1
	v_readlane_b32 s56, v133, 0
	v_readlane_b32 s57, v133, 16
	v_readlane_b32 s58, v133, 32
	v_readlane_b32 s59, v133, 48
	v_mov_b32_e32 v222, s57
	v_mov_b32_e32 v223, s59
	v_add_f32_e32 v222, s56, v222
	v_add_f32_e32 v223, s58, v223
	v_add_f32_e32 v133, v222, v223
	v_fmamk_f32 v133, v133, 0x3a800000, v215
	v_cmp_gt_f32_e32 vcc, s33, v133
	v_mul_f32_e32 v222, 0x4b800000, v133
	s_nop 0
	v_cndmask_b32_e32 v133, v133, v222, vcc
	v_rsq_f32_e32 v133, v133
	s_nop 0
	v_mul_f32_e32 v222, 0x45800000, v133
	v_cndmask_b32_e32 v220, v133, v222, vcc
	v_pk_mul_f32 v[168:169], v[168:169], v[220:221] op_sel_hi:[1,0]
	v_pk_mul_f32 v[170:171], v[170:171], v[220:221] op_sel_hi:[1,0]
	v_pk_mul_f32 v[172:173], v[172:173], v[220:221] op_sel_hi:[1,0]
	v_pk_mul_f32 v[174:175], v[174:175], v[220:221] op_sel_hi:[1,0]
	v_pk_mul_f32 v[176:177], v[176:177], v[220:221] op_sel_hi:[1,0]
	v_pk_mul_f32 v[178:179], v[178:179], v[220:221] op_sel_hi:[1,0]
	v_pk_mul_f32 v[180:181], v[180:181], v[220:221] op_sel_hi:[1,0]
	v_pk_mul_f32 v[182:183], v[182:183], v[220:221] op_sel_hi:[1,0]
	v_pk_fma_f32 v[168:169], v[184:185], v[168:169], v[200:201]
	v_pk_fma_f32 v[170:171], v[186:187], v[170:171], v[202:203]
	v_pk_fma_f32 v[172:173], v[188:189], v[172:173], v[204:205]
	v_pk_fma_f32 v[174:175], v[190:191], v[174:175], v[206:207]
	v_pk_fma_f32 v[176:177], v[192:193], v[176:177], v[226:227]
	v_pk_fma_f32 v[178:179], v[194:195], v[178:179], v[228:229]
	v_pk_fma_f32 v[180:181], v[196:197], v[180:181], v[230:231]
	v_pk_fma_f32 v[182:183], v[198:199], v[182:183], v[232:233]
	global_store_dwordx4 v212, v[168:171], s[64:65] offset:0
	global_store_dwordx4 v212, v[172:175], s[64:65] offset:1024
	global_store_dwordx4 v212, v[176:179], s[64:65] offset:2048
	global_store_dwordx4 v212, v[180:183], s[64:65] offset:3072
	v_cvt_pk_bf16_f32 v168, v168, v169
	v_cvt_pk_bf16_f32 v169, v170, v171
	v_cvt_pk_bf16_f32 v172, v172, v173
	v_cvt_pk_bf16_f32 v173, v174, v175
	v_cvt_pk_bf16_f32 v176, v176, v177
	v_cvt_pk_bf16_f32 v177, v178, v179
	v_cvt_pk_bf16_f32 v180, v180, v181
	v_cvt_pk_bf16_f32 v181, v182, v183
	global_store_dwordx2 v214, v[168:169], s[72:73] offset:2048
	global_store_dwordx2 v214, v[172:173], s[72:73] offset:2560
	global_store_dwordx2 v214, v[176:177], s[72:73] offset:3072
	global_store_dwordx2 v214, v[180:181], s[72:73] offset:3584
	s_xor_b64 s[22:23], exec, -1
	s_branch .LBB0_55

.LBB0_1608:
	s_mov_b32 s100, 0
	v_readlane_b32 s8, v252, 54
	v_readlane_b32 s9, v252, 55
	v_readlane_b32 s16, v251, 1
	s_lshl_b64 s[10:11], s[8:9], 2
	v_readlane_b32 s24, v251, 9
	v_readlane_b32 s25, v251, 10
	s_add_u32 s8, s24, s10
	v_readlane_b32 s26, v251, 11
	s_addc_u32 s9, s25, s11
	v_readlane_b32 s12, v252, 56
	v_readlane_b32 s27, v251, 12
	s_add_u32 s10, s26, s10
	v_readlane_b32 s13, v252, 57
	s_addc_u32 s11, s27, s11
	s_lshl_b64 s[12:13], s[12:13], 2
	s_add_u32 s12, s0, s12
	s_addc_u32 s13, s1, s13
	s_add_u32 s12, s12, 0x23f9a214
	s_addc_u32 s13, s13, 0
	v_readlane_b32 s17, v251, 2
	s_add_u32 s4, s4, 0x1000
	s_addc_u32 s5, s5, 0
	s_mov_b64 s[16:17], 0
	v_readlane_b32 s18, v251, 3
	v_readlane_b32 s19, v251, 4
	v_readlane_b32 s20, v251, 5
	v_readlane_b32 s21, v251, 6
	v_readlane_b32 s22, v251, 7
	v_readlane_b32 s23, v251, 8
	v_readlane_b32 s28, v251, 13
	v_readlane_b32 s29, v251, 14
	v_readlane_b32 s30, v251, 15
	v_readlane_b32 s31, v251, 16
	s_branch .LBB0_1610

.LBB0_1610:
	s_waitcnt lgkmcnt(0)
	s_barrier
	s_mov_b64 s[18:19], exec
	v_readlane_b32 s20, v251, 19
	v_readlane_b32 s21, v251, 20
	s_and_b64 s[20:21], s[18:19], s[20:21]
	s_mov_b64 exec, s[20:21]
	s_cbranch_execz .LBB0_1612
	s_waitcnt vmcnt(0)
	s_cmp_eq_u32 s100, 0
	s_cbranch_scc1 .Llnq_atomic_B
	v_mov_b32_e32 v0, v250
	s_branch .Llnq_have_B
.Llnq_atomic_B:
	v_mov_b64_e32 v[2:3], s[12:13]
	flat_atomic_add v0, v[2:3], v213 sc0
.Llnq_have_B:
	s_mov_b64 s[20:21], src_shared_base
	s_add_i32 s20, 0, 0x22ff0
	s_cmp_lg_u32 s20, -1
	s_cselect_b32 s20, s20, 0
	s_cselect_b32 s21, s21, 0
	v_mov_b32_e32 v2, s20
	v_mov_b32_e32 v3, s21
	s_waitcnt vmcnt(0) lgkmcnt(0)
	flat_store_dword v[2:3], v0 sc0 sc1
	s_waitcnt vmcnt(0)

.LBB0_1618:
	v_readlane_b32 s74, v251, 19
	v_readlane_b32 s75, v251, 20
	s_mov_b64 s[78:79], exec
	s_nop 3
	s_and_b64 exec, exec, s[74:75]
	global_atomic_add v250, v1, v213, s[12:13] sc0
	s_mov_b64 exec, s[78:79]
	s_mov_b32 s100, 1
	v_lshlrev_b32_e32 v212, 4, v219
	v_lshlrev_b32_e32 v214, 3, v219
	v_readfirstlane_b32 s42, v32
	v_readfirstlane_b32 s43, v33
	v_readfirstlane_b32 s66, v30
	v_readfirstlane_b32 s67, v31
	global_load_dwordx4 v[184:187], v[26:27], off offset:0
	global_load_dwordx4 v[188:191], v[26:27], off offset:1024
	global_load_dwordx4 v[192:195], v[26:27], off offset:2048
	global_load_dwordx4 v[196:199], v[26:27], off offset:3072
	global_load_dwordx4 v[200:203], v[28:29], off offset:0
	global_load_dwordx4 v[204:207], v[28:29], off offset:1024
	global_load_dwordx4 v[226:229], v[28:29], off offset:2048
	global_load_dwordx4 v[230:233], v[28:29], off offset:3072
	s_sub_u32 s42, s42, 0x1000
	s_subb_u32 s43, s43, 0
	global_load_dwordx4 v[2:5], v212, s[42:43] offset:0 sc1
	global_load_dwordx4 v[6:9], v212, s[42:43] offset:1024 sc1
	global_load_dwordx4 v[10:13], v212, s[42:43] offset:2048 sc1
	global_load_dwordx4 v[14:17], v212, s[42:43] offset:3072 sc1
	s_add_u32 s44, s42, 0x1000
	s_addc_u32 s45, s43, 0
	global_load_dwordx4 v[18:21], v212, s[44:45] offset:0 sc1
	global_load_dwordx4 v[22:25], v212, s[44:45] offset:1024 sc1
	global_load_dwordx4 v[34:37], v212, s[44:45] offset:2048 sc1
	global_load_dwordx4 v[38:41], v212, s[44:45] offset:3072 sc1
	s_add_u32 s46, s44, 0x1000
	s_addc_u32 s47, s45, 0
	global_load_dwordx4 v[44:47], v212, s[46:47] offset:0 sc1
	global_load_dwordx4 v[48:51], v212, s[46:47] offset:1024 sc1
	global_load_dwordx4 v[52:55], v212, s[46:47] offset:2048 sc1
	global_load_dwordx4 v[56:59], v212, s[46:47] offset:3072 sc1
	s_add_u32 s48, s46, 0x1000
	s_addc_u32 s49, s47, 0
	global_load_dwordx4 v[60:63], v212, s[48:49] offset:0 sc1
	global_load_dwordx4 v[64:67], v212, s[48:49] offset:1024 sc1
	global_load_dwordx4 v[94:97], v212, s[48:49] offset:2048 sc1
	global_load_dwordx4 v[98:101], v212, s[48:49] offset:3072 sc1
	s_add_u32 s50, s48, 0x1000
	s_addc_u32 s51, s49, 0
	global_load_dwordx4 v[102:105], v212, s[50:51] offset:0 sc1
	global_load_dwordx4 v[106:109], v212, s[50:51] offset:1024 sc1
	global_load_dwordx4 v[110:113], v212, s[50:51] offset:2048 sc1
	global_load_dwordx4 v[114:117], v212, s[50:51] offset:3072 sc1
	s_add_u32 s52, s50, 0x1000
	s_addc_u32 s53, s51, 0
	global_load_dwordx4 v[118:121], v212, s[52:53] offset:0 sc1
	global_load_dwordx4 v[122:125], v212, s[52:53] offset:1024 sc1
	global_load_dwordx4 v[144:147], v212, s[52:53] offset:2048 sc1
	global_load_dwordx4 v[148:151], v212, s[52:53] offset:3072 sc1
	s_add_u32 s62, s52, 0x1000
	s_addc_u32 s63, s53, 0
	global_load_dwordx4 v[152:155], v212, s[62:63] offset:0 sc1
	global_load_dwordx4 v[156:159], v212, s[62:63] offset:1024 sc1
	global_load_dwordx4 v[160:163], v212, s[62:63] offset:2048 sc1
	global_load_dwordx4 v[164:167], v212, s[62:63] offset:3072 sc1
	s_add_u32 s64, s62, 0x1000
	s_addc_u32 s65, s63, 0
	global_load_dwordx4 v[168:171], v212, s[64:65] offset:0 sc1
	global_load_dwordx4 v[172:175], v212, s[64:65] offset:1024 sc1
	global_load_dwordx4 v[176:179], v212, s[64:65] offset:2048 sc1
	global_load_dwordx4 v[180:183], v212, s[64:65] offset:3072 sc1
	s_add_u32 s66, s66, 0x1f80000
	s_addc_u32 s67, s67, 0
	s_add_u32 s68, s66, 0x1000
	s_addc_u32 s69, s67, 0
	s_add_u32 s70, s68, 0x1000
	s_addc_u32 s71, s69, 0
	s_add_u32 s72, s70, 0x1000
	s_addc_u32 s73, s71, 0
	s_waitcnt vmcnt(28)
	v_pk_add_f32 v[76:77], v[2:3], v[4:5]
	v_pk_add_f32 v[136:137], v[6:7], v[8:9]
	v_pk_add_f32 v[138:139], v[10:11], v[12:13]
	v_pk_add_f32 v[208:209], v[14:15], v[16:17]
	v_pk_add_f32 v[76:77], v[76:77], v[136:137]
	v_pk_add_f32 v[138:139], v[138:139], v[208:209]
	v_pk_add_f32 v[76:77], v[76:77], v[138:139]
	v_add_f32_e32 v131, v76, v77
	s_nop 1
	v_add_f32_dpp v131, v131, v131 quad_perm:[1,0,3,2] row_mask:0xf bank_mask:0xf bound_ctrl:1
	s_nop 1
	v_add_f32_dpp v131, v131, v131 quad_perm:[2,3,0,1] row_mask:0xf bank_mask:0xf bound_ctrl:1
	s_nop 1
	v_add_f32_dpp v131, v131, v131 row_half_mirror row_mask:0xf bank_mask:0xf bound_ctrl:1
	s_nop 1
	v_add_f32_dpp v131, v131, v131 row_mirror row_mask:0xf bank_mask:0xf bound_ctrl:1
	s_nop 1
	v_readlane_b32 s56, v131, 0
	v_readlane_b32 s57, v131, 16
	v_readlane_b32 s58, v131, 32
	v_readlane_b32 s59, v131, 48
	v_mov_b32_e32 v222, s57
	v_mov_b32_e32 v223, s59
	v_add_f32_e32 v222, s56, v222
	v_add_f32_e32 v223, s58, v223
	v_add_f32_e32 v131, v222, v223
	v_mul_f32_e32 v216, 0x3a800000, v131
	v_pk_add_f32 v[2:3], v[2:3], v[216:217] op_sel_hi:[1,0] neg_lo:[0,1] neg_hi:[0,1]
	v_pk_add_f32 v[4:5], v[4:5], v[216:217] op_sel_hi:[1,0] neg_lo:[0,1] neg_hi:[0,1]
	v_pk_add_f32 v[6:7], v[6:7], v[216:217] op_sel_hi:[1,0] neg_lo:[0,1] neg_hi:[0,1]
	v_pk_add_f32 v[8:9], v[8:9], v[216:217] op_sel_hi:[1,0] neg_lo:[0,1] neg_hi:[0,1]
	v_pk_add_f32 v[10:11], v[10:11], v[216:217] op_sel_hi:[1,0] neg_lo:[0,1] neg_hi:[0,1]
	v_pk_add_f32 v[12:13], v[12:13], v[216:217] op_sel_hi:[1,0] neg_lo:[0,1] neg_hi:[0,1]
	v_pk_add_f32 v[14:15], v[14:15], v[216:217] op_sel_hi:[1,0] neg_lo:[0,1] neg_hi:[0,1]
	v_pk_add_f32 v[16:17], v[16:17], v[216:217] op_sel_hi:[1,0] neg_lo:[0,1] neg_hi:[0,1]
	v_pk_mul_f32 v[76:77], v[2:3], v[2:3]
	v_pk_mul_f32 v[136:137], v[4:5], v[4:5]
	v_add_f32_e32 v133, v76, v77
	v_add_f32_e32 v133, v136, v133
	v_add_f32_e32 v133, v137, v133
	v_pk_mul_f32 v[76:77], v[6:7], v[6:7]
	v_pk_mul_f32 v[136:137], v[8:9], v[8:9]
	v_add_f32_e32 v133, v76, v133
	v_add_f32_e32 v133, v77, v133
	v_add_f32_e32 v133, v136, v133
	v_add_f32_e32 v133, v137, v133
	v_pk_mul_f32 v[76:77], v[10:11], v[10:11]
	v_pk_mul_f32 v[136:137], v[12:13], v[12:13]
	v_add_f32_e32 v133, v76, v133
	v_add_f32_e32 v133, v77, v133
	v_add_f32_e32 v133, v136, v133
	v_add_f32_e32 v133, v137, v133
	v_pk_mul_f32 v[76:77], v[14:15], v[14:15]
	v_pk_mul_f32 v[136:137], v[16:17], v[16:17]
	v_add_f32_e32 v133, v76, v133
	v_add_f32_e32 v133, v77, v133
	v_add_f32_e32 v133, v136, v133
	v_add_f32_e32 v133, v137, v133
	s_nop 1
	v_add_f32_dpp v133, v133, v133 quad_perm:[1,0,3,2] row_mask:0xf bank_mask:0xf bound_ctrl:1
	s_nop 1
	v_add_f32_dpp v133, v133, v133 quad_perm:[2,3,0,1] row_mask:0xf bank_mask:0xf bound_ctrl:1
	s_nop 1
	v_add_f32_dpp v133, v133, v133 row_half_mirror row_mask:0xf bank_mask:0xf bound_ctrl:1
	s_nop 1
	v_add_f32_dpp v133, v133, v133 row_mirror row_mask:0xf bank_mask:0xf bound_ctrl:1
	s_nop 1
	v_readlane_b32 s56, v133, 0
	v_readlane_b32 s57, v133, 16
	v_readlane_b32 s58, v133, 32
	v_readlane_b32 s59, v133, 48
	v_mov_b32_e32 v222, s57
	v_mov_b32_e32 v223, s59
	v_add_f32_e32 v222, s56, v222
	v_add_f32_e32 v223, s58, v223
	v_add_f32_e32 v133, v222, v223
	v_fmamk_f32 v133, v133, 0x3a800000, v215
	v_cmp_gt_f32_e32 vcc, s33, v133
	v_mul_f32_e32 v222, 0x4b800000, v133
	s_nop 0
	v_cndmask_b32_e32 v133, v133, v222, vcc
	v_rsq_f32_e32 v133, v133
	s_nop 0
	v_mul_f32_e32 v222, 0x45800000, v133
	v_cndmask_b32_e32 v220, v133, v222, vcc
	v_pk_mul_f32 v[2:3], v[2:3], v[220:221] op_sel_hi:[1,0]
	v_pk_mul_f32 v[4:5], v[4:5], v[220:221] op_sel_hi:[1,0]
	v_pk_mul_f32 v[6:7], v[6:7], v[220:221] op_sel_hi:[1,0]
	v_pk_mul_f32 v[8:9], v[8:9], v[220:221] op_sel_hi:[1,0]
	v_pk_mul_f32 v[10:11], v[10:11], v[220:221] op_sel_hi:[1,0]
	v_pk_mul_f32 v[12:13], v[12:13], v[220:221] op_sel_hi:[1,0]
	v_pk_mul_f32 v[14:15], v[14:15], v[220:221] op_sel_hi:[1,0]
	v_pk_mul_f32 v[16:17], v[16:17], v[220:221] op_sel_hi:[1,0]
	v_pk_fma_f32 v[2:3], v[184:185], v[2:3], v[200:201]
	v_pk_fma_f32 v[4:5], v[186:187], v[4:5], v[202:203]
	v_pk_fma_f32 v[6:7], v[188:189], v[6:7], v[204:205]
	v_pk_fma_f32 v[8:9], v[190:191], v[8:9], v[206:207]
	v_pk_fma_f32 v[10:11], v[192:193], v[10:11], v[226:227]
	v_pk_fma_f32 v[12:13], v[194:195], v[12:13], v[228:229]
	v_pk_fma_f32 v[14:15], v[196:197], v[14:15], v[230:231]
	v_pk_fma_f32 v[16:17], v[198:199], v[16:17], v[232:233]
	global_store_dwordx4 v212, v[2:5], s[42:43] offset:0
	global_store_dwordx4 v212, v[6:9], s[42:43] offset:1024
	global_store_dwordx4 v212, v[10:13], s[42:43] offset:2048
	global_store_dwordx4 v212, v[14:17], s[42:43] offset:3072
	v_cvt_pk_bf16_f32 v2, v2, v3
	v_cvt_pk_bf16_f32 v3, v4, v5
	v_cvt_pk_bf16_f32 v6, v6, v7
	v_cvt_pk_bf16_f32 v7, v8, v9
	v_cvt_pk_bf16_f32 v10, v10, v11
	v_cvt_pk_bf16_f32 v11, v12, v13
	v_cvt_pk_bf16_f32 v14, v14, v15
	v_cvt_pk_bf16_f32 v15, v16, v17
	global_store_dwordx2 v214, v[2:3], s[66:67] offset:0
	global_store_dwordx2 v214, v[6:7], s[66:67] offset:512
	global_store_dwordx2 v214, v[10:11], s[66:67] offset:1024
	global_store_dwordx2 v214, v[14:15], s[66:67] offset:1536
	s_waitcnt vmcnt(32)
	v_pk_add_f32 v[76:77], v[18:19], v[20:21]
	v_pk_add_f32 v[136:137], v[22:23], v[24:25]
	v_pk_add_f32 v[138:139], v[34:35], v[36:37]
	v_pk_add_f32 v[208:209], v[38:39], v[40:41]
	v_pk_add_f32 v[76:77], v[76:77], v[136:137]
	v_pk_add_f32 v[138:139], v[138:139], v[208:209]
	v_pk_add_f32 v[76:77], v[76:77], v[138:139]
	v_add_f32_e32 v131, v76, v77
	s_nop 1
	v_add_f32_dpp v131, v131, v131 quad_perm:[1,0,3,2] row_mask:0xf bank_mask:0xf bound_ctrl:1
	s_nop 1
	v_add_f32_dpp v131, v131, v131 quad_perm:[2,3,0,1] row_mask:0xf bank_mask:0xf bound_ctrl:1
	s_nop 1
	v_add_f32_dpp v131, v131, v131 row_half_mirror row_mask:0xf bank_mask:0xf bound_ctrl:1
	s_nop 1
	v_add_f32_dpp v131, v131, v131 row_mirror row_mask:0xf bank_mask:0xf bound_ctrl:1
	s_nop 1
	v_readlane_b32 s56, v131, 0
	v_readlane_b32 s57, v131, 16
	v_readlane_b32 s58, v131, 32
	v_readlane_b32 s59, v131, 48
	v_mov_b32_e32 v222, s57
	v_mov_b32_e32 v223, s59
	v_add_f32_e32 v222, s56, v222
	v_add_f32_e32 v223, s58, v223
	v_add_f32_e32 v131, v222, v223
	v_mul_f32_e32 v216, 0x3a800000, v131
	v_pk_add_f32 v[18:19], v[18:19], v[216:217] op_sel_hi:[1,0] neg_lo:[0,1] neg_hi:[0,1]
	v_pk_add_f32 v[20:21], v[20:21], v[216:217] op_sel_hi:[1,0] neg_lo:[0,1] neg_hi:[0,1]
	v_pk_add_f32 v[22:23], v[22:23], v[216:217] op_sel_hi:[1,0] neg_lo:[0,1] neg_hi:[0,1]
	v_pk_add_f32 v[24:25], v[24:25], v[216:217] op_sel_hi:[1,0] neg_lo:[0,1] neg_hi:[0,1]
	v_pk_add_f32 v[34:35], v[34:35], v[216:217] op_sel_hi:[1,0] neg_lo:[0,1] neg_hi:[0,1]
	v_pk_add_f32 v[36:37], v[36:37], v[216:217] op_sel_hi:[1,0] neg_lo:[0,1] neg_hi:[0,1]
	v_pk_add_f32 v[38:39], v[38:39], v[216:217] op_sel_hi:[1,0] neg_lo:[0,1] neg_hi:[0,1]
	v_pk_add_f32 v[40:41], v[40:41], v[216:217] op_sel_hi:[1,0] neg_lo:[0,1] neg_hi:[0,1]
	v_pk_mul_f32 v[76:77], v[18:19], v[18:19]
	v_pk_mul_f32 v[136:137], v[20:21], v[20:21]
	v_add_f32_e32 v133, v76, v77
	v_add_f32_e32 v133, v136, v133
	v_add_f32_e32 v133, v137, v133
	v_pk_mul_f32 v[76:77], v[22:23], v[22:23]
	v_pk_mul_f32 v[136:137], v[24:25], v[24:25]
	v_add_f32_e32 v133, v76, v133
	v_add_f32_e32 v133, v77, v133
	v_add_f32_e32 v133, v136, v133
	v_add_f32_e32 v133, v137, v133
	v_pk_mul_f32 v[76:77], v[34:35], v[34:35]
	v_pk_mul_f32 v[136:137], v[36:37], v[36:37]
	v_add_f32_e32 v133, v76, v133
	v_add_f32_e32 v133, v77, v133
	v_add_f32_e32 v133, v136, v133
	v_add_f32_e32 v133, v137, v133
	v_pk_mul_f32 v[76:77], v[38:39], v[38:39]
	v_pk_mul_f32 v[136:137], v[40:41], v[40:41]
	v_add_f32_e32 v133, v76, v133
	v_add_f32_e32 v133, v77, v133
	v_add_f32_e32 v133, v136, v133
	v_add_f32_e32 v133, v137, v133
	s_nop 1
	v_add_f32_dpp v133, v133, v133 quad_perm:[1,0,3,2] row_mask:0xf bank_mask:0xf bound_ctrl:1
	s_nop 1
	v_add_f32_dpp v133, v133, v133 quad_perm:[2,3,0,1] row_mask:0xf bank_mask:0xf bound_ctrl:1
	s_nop 1
	v_add_f32_dpp v133, v133, v133 row_half_mirror row_mask:0xf bank_mask:0xf bound_ctrl:1
	s_nop 1
	v_add_f32_dpp v133, v133, v133 row_mirror row_mask:0xf bank_mask:0xf bound_ctrl:1
	s_nop 1
	v_readlane_b32 s56, v133, 0
	v_readlane_b32 s57, v133, 16
	v_readlane_b32 s58, v133, 32
	v_readlane_b32 s59, v133, 48
	v_mov_b32_e32 v222, s57
	v_mov_b32_e32 v223, s59
	v_add_f32_e32 v222, s56, v222
	v_add_f32_e32 v223, s58, v223
	v_add_f32_e32 v133, v222, v223
	v_fmamk_f32 v133, v133, 0x3a800000, v215
	v_cmp_gt_f32_e32 vcc, s33, v133
	v_mul_f32_e32 v222, 0x4b800000, v133
	s_nop 0
	v_cndmask_b32_e32 v133, v133, v222, vcc
	v_rsq_f32_e32 v133, v133
	s_nop 0
	v_mul_f32_e32 v222, 0x45800000, v133
	v_cndmask_b32_e32 v220, v133, v222, vcc
	v_pk_mul_f32 v[18:19], v[18:19], v[220:221] op_sel_hi:[1,0]
	v_pk_mul_f32 v[20:21], v[20:21], v[220:221] op_sel_hi:[1,0]
	v_pk_mul_f32 v[22:23], v[22:23], v[220:221] op_sel_hi:[1,0]
	v_pk_mul_f32 v[24:25], v[24:25], v[220:221] op_sel_hi:[1,0]
	v_pk_mul_f32 v[34:35], v[34:35], v[220:221] op_sel_hi:[1,0]
	v_pk_mul_f32 v[36:37], v[36:37], v[220:221] op_sel_hi:[1,0]
	v_pk_mul_f32 v[38:39], v[38:39], v[220:221] op_sel_hi:[1,0]
	v_pk_mul_f32 v[40:41], v[40:41], v[220:221] op_sel_hi:[1,0]
	v_pk_fma_f32 v[18:19], v[184:185], v[18:19], v[200:201]
	v_pk_fma_f32 v[20:21], v[186:187], v[20:21], v[202:203]
	v_pk_fma_f32 v[22:23], v[188:189], v[22:23], v[204:205]
	v_pk_fma_f32 v[24:25], v[190:191], v[24:25], v[206:207]
	v_pk_fma_f32 v[34:35], v[192:193], v[34:35], v[226:227]
	v_pk_fma_f32 v[36:37], v[194:195], v[36:37], v[228:229]
	v_pk_fma_f32 v[38:39], v[196:197], v[38:39], v[230:231]
	v_pk_fma_f32 v[40:41], v[198:199], v[40:41], v[232:233]
	global_store_dwordx4 v212, v[18:21], s[44:45] offset:0
	global_store_dwordx4 v212, v[22:25], s[44:45] offset:1024
	global_store_dwordx4 v212, v[34:37], s[44:45] offset:2048
	global_store_dwordx4 v212, v[38:41], s[44:45] offset:3072
	v_cvt_pk_bf16_f32 v18, v18, v19
	v_cvt_pk_bf16_f32 v19, v20, v21
	v_cvt_pk_bf16_f32 v22, v22, v23
	v_cvt_pk_bf16_f32 v23, v24, v25
	v_cvt_pk_bf16_f32 v34, v34, v35
	v_cvt_pk_bf16_f32 v35, v36, v37
	v_cvt_pk_bf16_f32 v38, v38, v39
	v_cvt_pk_bf16_f32 v39, v40, v41
	global_store_dwordx2 v214, v[18:19], s[66:67] offset:2048
	global_store_dwordx2 v214, v[22:23], s[66:67] offset:2560
	global_store_dwordx2 v214, v[34:35], s[66:67] offset:3072
	global_store_dwordx2 v214, v[38:39], s[66:67] offset:3584
	s_waitcnt vmcnt(36)
	v_pk_add_f32 v[76:77], v[44:45], v[46:47]
	v_pk_add_f32 v[136:137], v[48:49], v[50:51]
	v_pk_add_f32 v[138:139], v[52:53], v[54:55]
	v_pk_add_f32 v[208:209], v[56:57], v[58:59]
	v_pk_add_f32 v[76:77], v[76:77], v[136:137]
	v_pk_add_f32 v[138:139], v[138:139], v[208:209]
	v_pk_add_f32 v[76:77], v[76:77], v[138:139]
	v_add_f32_e32 v131, v76, v77
	s_nop 1
	v_add_f32_dpp v131, v131, v131 quad_perm:[1,0,3,2] row_mask:0xf bank_mask:0xf bound_ctrl:1
	s_nop 1
	v_add_f32_dpp v131, v131, v131 quad_perm:[2,3,0,1] row_mask:0xf bank_mask:0xf bound_ctrl:1
	s_nop 1
	v_add_f32_dpp v131, v131, v131 row_half_mirror row_mask:0xf bank_mask:0xf bound_ctrl:1
	s_nop 1
	v_add_f32_dpp v131, v131, v131 row_mirror row_mask:0xf bank_mask:0xf bound_ctrl:1
	s_nop 1
	v_readlane_b32 s56, v131, 0
	v_readlane_b32 s57, v131, 16
	v_readlane_b32 s58, v131, 32
	v_readlane_b32 s59, v131, 48
	v_mov_b32_e32 v222, s57
	v_mov_b32_e32 v223, s59
	v_add_f32_e32 v222, s56, v222
	v_add_f32_e32 v223, s58, v223
	v_add_f32_e32 v131, v222, v223
	v_mul_f32_e32 v216, 0x3a800000, v131
	v_pk_add_f32 v[44:45], v[44:45], v[216:217] op_sel_hi:[1,0] neg_lo:[0,1] neg_hi:[0,1]
	v_pk_add_f32 v[46:47], v[46:47], v[216:217] op_sel_hi:[1,0] neg_lo:[0,1] neg_hi:[0,1]
	v_pk_add_f32 v[48:49], v[48:49], v[216:217] op_sel_hi:[1,0] neg_lo:[0,1] neg_hi:[0,1]
	v_pk_add_f32 v[50:51], v[50:51], v[216:217] op_sel_hi:[1,0] neg_lo:[0,1] neg_hi:[0,1]
	v_pk_add_f32 v[52:53], v[52:53], v[216:217] op_sel_hi:[1,0] neg_lo:[0,1] neg_hi:[0,1]
	v_pk_add_f32 v[54:55], v[54:55], v[216:217] op_sel_hi:[1,0] neg_lo:[0,1] neg_hi:[0,1]
	v_pk_add_f32 v[56:57], v[56:57], v[216:217] op_sel_hi:[1,0] neg_lo:[0,1] neg_hi:[0,1]
	v_pk_add_f32 v[58:59], v[58:59], v[216:217] op_sel_hi:[1,0] neg_lo:[0,1] neg_hi:[0,1]
	v_pk_mul_f32 v[76:77], v[44:45], v[44:45]
	v_pk_mul_f32 v[136:137], v[46:47], v[46:47]
	v_add_f32_e32 v133, v76, v77
	v_add_f32_e32 v133, v136, v133
	v_add_f32_e32 v133, v137, v133
	v_pk_mul_f32 v[76:77], v[48:49], v[48:49]
	v_pk_mul_f32 v[136:137], v[50:51], v[50:51]
	v_add_f32_e32 v133, v76, v133
	v_add_f32_e32 v133, v77, v133
	v_add_f32_e32 v133, v136, v133
	v_add_f32_e32 v133, v137, v133
	v_pk_mul_f32 v[76:77], v[52:53], v[52:53]
	v_pk_mul_f32 v[136:137], v[54:55], v[54:55]
	v_add_f32_e32 v133, v76, v133
	v_add_f32_e32 v133, v77, v133
	v_add_f32_e32 v133, v136, v133
	v_add_f32_e32 v133, v137, v133
	v_pk_mul_f32 v[76:77], v[56:57], v[56:57]
	v_pk_mul_f32 v[136:137], v[58:59], v[58:59]
	v_add_f32_e32 v133, v76, v133
	v_add_f32_e32 v133, v77, v133
	v_add_f32_e32 v133, v136, v133
	v_add_f32_e32 v133, v137, v133
	s_nop 1
	v_add_f32_dpp v133, v133, v133 quad_perm:[1,0,3,2] row_mask:0xf bank_mask:0xf bound_ctrl:1
	s_nop 1
	v_add_f32_dpp v133, v133, v133 quad_perm:[2,3,0,1] row_mask:0xf bank_mask:0xf bound_ctrl:1
	s_nop 1
	v_add_f32_dpp v133, v133, v133 row_half_mirror row_mask:0xf bank_mask:0xf bound_ctrl:1
	s_nop 1
	v_add_f32_dpp v133, v133, v133 row_mirror row_mask:0xf bank_mask:0xf bound_ctrl:1
	s_nop 1
	v_readlane_b32 s56, v133, 0
	v_readlane_b32 s57, v133, 16
	v_readlane_b32 s58, v133, 32
	v_readlane_b32 s59, v133, 48
	v_mov_b32_e32 v222, s57
	v_mov_b32_e32 v223, s59
	v_add_f32_e32 v222, s56, v222
	v_add_f32_e32 v223, s58, v223
	v_add_f32_e32 v133, v222, v223
	v_fmamk_f32 v133, v133, 0x3a800000, v215
	v_cmp_gt_f32_e32 vcc, s33, v133
	v_mul_f32_e32 v222, 0x4b800000, v133
	s_nop 0
	v_cndmask_b32_e32 v133, v133, v222, vcc
	v_rsq_f32_e32 v133, v133
	s_nop 0
	v_mul_f32_e32 v222, 0x45800000, v133
	v_cndmask_b32_e32 v220, v133, v222, vcc
	v_pk_mul_f32 v[44:45], v[44:45], v[220:221] op_sel_hi:[1,0]
	v_pk_mul_f32 v[46:47], v[46:47], v[220:221] op_sel_hi:[1,0]
	v_pk_mul_f32 v[48:49], v[48:49], v[220:221] op_sel_hi:[1,0]
	v_pk_mul_f32 v[50:51], v[50:51], v[220:221] op_sel_hi:[1,0]
	v_pk_mul_f32 v[52:53], v[52:53], v[220:221] op_sel_hi:[1,0]
	v_pk_mul_f32 v[54:55], v[54:55], v[220:221] op_sel_hi:[1,0]
	v_pk_mul_f32 v[56:57], v[56:57], v[220:221] op_sel_hi:[1,0]
	v_pk_mul_f32 v[58:59], v[58:59], v[220:221] op_sel_hi:[1,0]
	v_pk_fma_f32 v[44:45], v[184:185], v[44:45], v[200:201]
	v_pk_fma_f32 v[46:47], v[186:187], v[46:47], v[202:203]
	v_pk_fma_f32 v[48:49], v[188:189], v[48:49], v[204:205]
	v_pk_fma_f32 v[50:51], v[190:191], v[50:51], v[206:207]
	v_pk_fma_f32 v[52:53], v[192:193], v[52:53], v[226:227]
	v_pk_fma_f32 v[54:55], v[194:195], v[54:55], v[228:229]
	v_pk_fma_f32 v[56:57], v[196:197], v[56:57], v[230:231]
	v_pk_fma_f32 v[58:59], v[198:199], v[58:59], v[232:233]
	global_store_dwordx4 v212, v[44:47], s[46:47] offset:0
	global_store_dwordx4 v212, v[48:51], s[46:47] offset:1024
	global_store_dwordx4 v212, v[52:55], s[46:47] offset:2048
	global_store_dwordx4 v212, v[56:59], s[46:47] offset:3072
	v_cvt_pk_bf16_f32 v44, v44, v45
	v_cvt_pk_bf16_f32 v45, v46, v47
	v_cvt_pk_bf16_f32 v48, v48, v49
	v_cvt_pk_bf16_f32 v49, v50, v51
	v_cvt_pk_bf16_f32 v52, v52, v53
	v_cvt_pk_bf16_f32 v53, v54, v55
	v_cvt_pk_bf16_f32 v56, v56, v57
	v_cvt_pk_bf16_f32 v57, v58, v59
	global_store_dwordx2 v214, v[44:45], s[68:69] offset:0
	global_store_dwordx2 v214, v[48:49], s[68:69] offset:512
	global_store_dwordx2 v214, v[52:53], s[68:69] offset:1024
	global_store_dwordx2 v214, v[56:57], s[68:69] offset:1536
	s_waitcnt vmcnt(40)
	v_pk_add_f32 v[76:77], v[60:61], v[62:63]
	v_pk_add_f32 v[136:137], v[64:65], v[66:67]
	v_pk_add_f32 v[138:139], v[94:95], v[96:97]
	v_pk_add_f32 v[208:209], v[98:99], v[100:101]
	v_pk_add_f32 v[76:77], v[76:77], v[136:137]
	v_pk_add_f32 v[138:139], v[138:139], v[208:209]
	v_pk_add_f32 v[76:77], v[76:77], v[138:139]
	v_add_f32_e32 v131, v76, v77
	s_nop 1
	v_add_f32_dpp v131, v131, v131 quad_perm:[1,0,3,2] row_mask:0xf bank_mask:0xf bound_ctrl:1
	s_nop 1
	v_add_f32_dpp v131, v131, v131 quad_perm:[2,3,0,1] row_mask:0xf bank_mask:0xf bound_ctrl:1
	s_nop 1
	v_add_f32_dpp v131, v131, v131 row_half_mirror row_mask:0xf bank_mask:0xf bound_ctrl:1
	s_nop 1
	v_add_f32_dpp v131, v131, v131 row_mirror row_mask:0xf bank_mask:0xf bound_ctrl:1
	s_nop 1
	v_readlane_b32 s56, v131, 0
	v_readlane_b32 s57, v131, 16
	v_readlane_b32 s58, v131, 32
	v_readlane_b32 s59, v131, 48
	v_mov_b32_e32 v222, s57
	v_mov_b32_e32 v223, s59
	v_add_f32_e32 v222, s56, v222
	v_add_f32_e32 v223, s58, v223
	v_add_f32_e32 v131, v222, v223
	v_mul_f32_e32 v216, 0x3a800000, v131
	v_pk_add_f32 v[60:61], v[60:61], v[216:217] op_sel_hi:[1,0] neg_lo:[0,1] neg_hi:[0,1]
	v_pk_add_f32 v[62:63], v[62:63], v[216:217] op_sel_hi:[1,0] neg_lo:[0,1] neg_hi:[0,1]
	v_pk_add_f32 v[64:65], v[64:65], v[216:217] op_sel_hi:[1,0] neg_lo:[0,1] neg_hi:[0,1]
	v_pk_add_f32 v[66:67], v[66:67], v[216:217] op_sel_hi:[1,0] neg_lo:[0,1] neg_hi:[0,1]
	v_pk_add_f32 v[94:95], v[94:95], v[216:217] op_sel_hi:[1,0] neg_lo:[0,1] neg_hi:[0,1]
	v_pk_add_f32 v[96:97], v[96:97], v[216:217] op_sel_hi:[1,0] neg_lo:[0,1] neg_hi:[0,1]
	v_pk_add_f32 v[98:99], v[98:99], v[216:217] op_sel_hi:[1,0] neg_lo:[0,1] neg_hi:[0,1]
	v_pk_add_f32 v[100:101], v[100:101], v[216:217] op_sel_hi:[1,0] neg_lo:[0,1] neg_hi:[0,1]
	v_pk_mul_f32 v[76:77], v[60:61], v[60:61]
	v_pk_mul_f32 v[136:137], v[62:63], v[62:63]
	v_add_f32_e32 v133, v76, v77
	v_add_f32_e32 v133, v136, v133
	v_add_f32_e32 v133, v137, v133
	v_pk_mul_f32 v[76:77], v[64:65], v[64:65]
	v_pk_mul_f32 v[136:137], v[66:67], v[66:67]
	v_add_f32_e32 v133, v76, v133
	v_add_f32_e32 v133, v77, v133
	v_add_f32_e32 v133, v136, v133
	v_add_f32_e32 v133, v137, v133
	v_pk_mul_f32 v[76:77], v[94:95], v[94:95]
	v_pk_mul_f32 v[136:137], v[96:97], v[96:97]
	v_add_f32_e32 v133, v76, v133
	v_add_f32_e32 v133, v77, v133
	v_add_f32_e32 v133, v136, v133
	v_add_f32_e32 v133, v137, v133
	v_pk_mul_f32 v[76:77], v[98:99], v[98:99]
	v_pk_mul_f32 v[136:137], v[100:101], v[100:101]
	v_add_f32_e32 v133, v76, v133
	v_add_f32_e32 v133, v77, v133
	v_add_f32_e32 v133, v136, v133
	v_add_f32_e32 v133, v137, v133
	s_nop 1
	v_add_f32_dpp v133, v133, v133 quad_perm:[1,0,3,2] row_mask:0xf bank_mask:0xf bound_ctrl:1
	s_nop 1
	v_add_f32_dpp v133, v133, v133 quad_perm:[2,3,0,1] row_mask:0xf bank_mask:0xf bound_ctrl:1
	s_nop 1
	v_add_f32_dpp v133, v133, v133 row_half_mirror row_mask:0xf bank_mask:0xf bound_ctrl:1
	s_nop 1
	v_add_f32_dpp v133, v133, v133 row_mirror row_mask:0xf bank_mask:0xf bound_ctrl:1
	s_nop 1
	v_readlane_b32 s56, v133, 0
	v_readlane_b32 s57, v133, 16
	v_readlane_b32 s58, v133, 32
	v_readlane_b32 s59, v133, 48
	v_mov_b32_e32 v222, s57
	v_mov_b32_e32 v223, s59
	v_add_f32_e32 v222, s56, v222
	v_add_f32_e32 v223, s58, v223
	v_add_f32_e32 v133, v222, v223
	v_fmamk_f32 v133, v133, 0x3a800000, v215
	v_cmp_gt_f32_e32 vcc, s33, v133
	v_mul_f32_e32 v222, 0x4b800000, v133
	s_nop 0
	v_cndmask_b32_e32 v133, v133, v222, vcc
	v_rsq_f32_e32 v133, v133
	s_nop 0
	v_mul_f32_e32 v222, 0x45800000, v133
	v_cndmask_b32_e32 v220, v133, v222, vcc
	v_pk_mul_f32 v[60:61], v[60:61], v[220:221] op_sel_hi:[1,0]
	v_pk_mul_f32 v[62:63], v[62:63], v[220:221] op_sel_hi:[1,0]
	v_pk_mul_f32 v[64:65], v[64:65], v[220:221] op_sel_hi:[1,0]
	v_pk_mul_f32 v[66:67], v[66:67], v[220:221] op_sel_hi:[1,0]
	v_pk_mul_f32 v[94:95], v[94:95], v[220:221] op_sel_hi:[1,0]
	v_pk_mul_f32 v[96:97], v[96:97], v[220:221] op_sel_hi:[1,0]
	v_pk_mul_f32 v[98:99], v[98:99], v[220:221] op_sel_hi:[1,0]
	v_pk_mul_f32 v[100:101], v[100:101], v[220:221] op_sel_hi:[1,0]
	v_pk_fma_f32 v[60:61], v[184:185], v[60:61], v[200:201]
	v_pk_fma_f32 v[62:63], v[186:187], v[62:63], v[202:203]
	v_pk_fma_f32 v[64:65], v[188:189], v[64:65], v[204:205]
	v_pk_fma_f32 v[66:67], v[190:191], v[66:67], v[206:207]
	v_pk_fma_f32 v[94:95], v[192:193], v[94:95], v[226:227]
	v_pk_fma_f32 v[96:97], v[194:195], v[96:97], v[228:229]
	v_pk_fma_f32 v[98:99], v[196:197], v[98:99], v[230:231]
	v_pk_fma_f32 v[100:101], v[198:199], v[100:101], v[232:233]
	global_store_dwordx4 v212, v[60:63], s[48:49] offset:0
	global_store_dwordx4 v212, v[64:67], s[48:49] offset:1024
	global_store_dwordx4 v212, v[94:97], s[48:49] offset:2048
	global_store_dwordx4 v212, v[98:101], s[48:49] offset:3072
	v_cvt_pk_bf16_f32 v60, v60, v61
	v_cvt_pk_bf16_f32 v61, v62, v63
	v_cvt_pk_bf16_f32 v64, v64, v65
	v_cvt_pk_bf16_f32 v65, v66, v67
	v_cvt_pk_bf16_f32 v94, v94, v95
	v_cvt_pk_bf16_f32 v95, v96, v97
	v_cvt_pk_bf16_f32 v98, v98, v99
	v_cvt_pk_bf16_f32 v99, v100, v101
	global_store_dwordx2 v214, v[60:61], s[68:69] offset:2048
	global_store_dwordx2 v214, v[64:65], s[68:69] offset:2560
	global_store_dwordx2 v214, v[94:95], s[68:69] offset:3072
	global_store_dwordx2 v214, v[98:99], s[68:69] offset:3584
	s_waitcnt vmcnt(44)
	v_pk_add_f32 v[76:77], v[102:103], v[104:105]
	v_pk_add_f32 v[136:137], v[106:107], v[108:109]
	v_pk_add_f32 v[138:139], v[110:111], v[112:113]
	v_pk_add_f32 v[208:209], v[114:115], v[116:117]
	v_pk_add_f32 v[76:77], v[76:77], v[136:137]
	v_pk_add_f32 v[138:139], v[138:139], v[208:209]
	v_pk_add_f32 v[76:77], v[76:77], v[138:139]
	v_add_f32_e32 v131, v76, v77
	s_nop 1
	v_add_f32_dpp v131, v131, v131 quad_perm:[1,0,3,2] row_mask:0xf bank_mask:0xf bound_ctrl:1
	s_nop 1
	v_add_f32_dpp v131, v131, v131 quad_perm:[2,3,0,1] row_mask:0xf bank_mask:0xf bound_ctrl:1
	s_nop 1
	v_add_f32_dpp v131, v131, v131 row_half_mirror row_mask:0xf bank_mask:0xf bound_ctrl:1
	s_nop 1
	v_add_f32_dpp v131, v131, v131 row_mirror row_mask:0xf bank_mask:0xf bound_ctrl:1
	s_nop 1
	v_readlane_b32 s56, v131, 0
	v_readlane_b32 s57, v131, 16
	v_readlane_b32 s58, v131, 32
	v_readlane_b32 s59, v131, 48
	v_mov_b32_e32 v222, s57
	v_mov_b32_e32 v223, s59
	v_add_f32_e32 v222, s56, v222
	v_add_f32_e32 v223, s58, v223
	v_add_f32_e32 v131, v222, v223
	v_mul_f32_e32 v216, 0x3a800000, v131
	v_pk_add_f32 v[102:103], v[102:103], v[216:217] op_sel_hi:[1,0] neg_lo:[0,1] neg_hi:[0,1]
	v_pk_add_f32 v[104:105], v[104:105], v[216:217] op_sel_hi:[1,0] neg_lo:[0,1] neg_hi:[0,1]
	v_pk_add_f32 v[106:107], v[106:107], v[216:217] op_sel_hi:[1,0] neg_lo:[0,1] neg_hi:[0,1]
	v_pk_add_f32 v[108:109], v[108:109], v[216:217] op_sel_hi:[1,0] neg_lo:[0,1] neg_hi:[0,1]
	v_pk_add_f32 v[110:111], v[110:111], v[216:217] op_sel_hi:[1,0] neg_lo:[0,1] neg_hi:[0,1]
	v_pk_add_f32 v[112:113], v[112:113], v[216:217] op_sel_hi:[1,0] neg_lo:[0,1] neg_hi:[0,1]
	v_pk_add_f32 v[114:115], v[114:115], v[216:217] op_sel_hi:[1,0] neg_lo:[0,1] neg_hi:[0,1]
	v_pk_add_f32 v[116:117], v[116:117], v[216:217] op_sel_hi:[1,0] neg_lo:[0,1] neg_hi:[0,1]
	v_pk_mul_f32 v[76:77], v[102:103], v[102:103]
	v_pk_mul_f32 v[136:137], v[104:105], v[104:105]
	v_add_f32_e32 v133, v76, v77
	v_add_f32_e32 v133, v136, v133
	v_add_f32_e32 v133, v137, v133
	v_pk_mul_f32 v[76:77], v[106:107], v[106:107]
	v_pk_mul_f32 v[136:137], v[108:109], v[108:109]
	v_add_f32_e32 v133, v76, v133
	v_add_f32_e32 v133, v77, v133
	v_add_f32_e32 v133, v136, v133
	v_add_f32_e32 v133, v137, v133
	v_pk_mul_f32 v[76:77], v[110:111], v[110:111]
	v_pk_mul_f32 v[136:137], v[112:113], v[112:113]
	v_add_f32_e32 v133, v76, v133
	v_add_f32_e32 v133, v77, v133
	v_add_f32_e32 v133, v136, v133
	v_add_f32_e32 v133, v137, v133
	v_pk_mul_f32 v[76:77], v[114:115], v[114:115]
	v_pk_mul_f32 v[136:137], v[116:117], v[116:117]
	v_add_f32_e32 v133, v76, v133
	v_add_f32_e32 v133, v77, v133
	v_add_f32_e32 v133, v136, v133
	v_add_f32_e32 v133, v137, v133
	s_nop 1
	v_add_f32_dpp v133, v133, v133 quad_perm:[1,0,3,2] row_mask:0xf bank_mask:0xf bound_ctrl:1
	s_nop 1
	v_add_f32_dpp v133, v133, v133 quad_perm:[2,3,0,1] row_mask:0xf bank_mask:0xf bound_ctrl:1
	s_nop 1
	v_add_f32_dpp v133, v133, v133 row_half_mirror row_mask:0xf bank_mask:0xf bound_ctrl:1
	s_nop 1
	v_add_f32_dpp v133, v133, v133 row_mirror row_mask:0xf bank_mask:0xf bound_ctrl:1
	s_nop 1
	v_readlane_b32 s56, v133, 0
	v_readlane_b32 s57, v133, 16
	v_readlane_b32 s58, v133, 32
	v_readlane_b32 s59, v133, 48
	v_mov_b32_e32 v222, s57
	v_mov_b32_e32 v223, s59
	v_add_f32_e32 v222, s56, v222
	v_add_f32_e32 v223, s58, v223
	v_add_f32_e32 v133, v222, v223
	v_fmamk_f32 v133, v133, 0x3a800000, v215
	v_cmp_gt_f32_e32 vcc, s33, v133
	v_mul_f32_e32 v222, 0x4b800000, v133
	s_nop 0
	v_cndmask_b32_e32 v133, v133, v222, vcc
	v_rsq_f32_e32 v133, v133
	s_nop 0
	v_mul_f32_e32 v222, 0x45800000, v133
	v_cndmask_b32_e32 v220, v133, v222, vcc
	v_pk_mul_f32 v[102:103], v[102:103], v[220:221] op_sel_hi:[1,0]
	v_pk_mul_f32 v[104:105], v[104:105], v[220:221] op_sel_hi:[1,0]
	v_pk_mul_f32 v[106:107], v[106:107], v[220:221] op_sel_hi:[1,0]
	v_pk_mul_f32 v[108:109], v[108:109], v[220:221] op_sel_hi:[1,0]
	v_pk_mul_f32 v[110:111], v[110:111], v[220:221] op_sel_hi:[1,0]
	v_pk_mul_f32 v[112:113], v[112:113], v[220:221] op_sel_hi:[1,0]
	v_pk_mul_f32 v[114:115], v[114:115], v[220:221] op_sel_hi:[1,0]
	v_pk_mul_f32 v[116:117], v[116:117], v[220:221] op_sel_hi:[1,0]
	v_pk_fma_f32 v[102:103], v[184:185], v[102:103], v[200:201]
	v_pk_fma_f32 v[104:105], v[186:187], v[104:105], v[202:203]
	v_pk_fma_f32 v[106:107], v[188:189], v[106:107], v[204:205]
	v_pk_fma_f32 v[108:109], v[190:191], v[108:109], v[206:207]
	v_pk_fma_f32 v[110:111], v[192:193], v[110:111], v[226:227]
	v_pk_fma_f32 v[112:113], v[194:195], v[112:113], v[228:229]
	v_pk_fma_f32 v[114:115], v[196:197], v[114:115], v[230:231]
	v_pk_fma_f32 v[116:117], v[198:199], v[116:117], v[232:233]
	global_store_dwordx4 v212, v[102:105], s[50:51] offset:0
	global_store_dwordx4 v212, v[106:109], s[50:51] offset:1024
	global_store_dwordx4 v212, v[110:113], s[50:51] offset:2048
	global_store_dwordx4 v212, v[114:117], s[50:51] offset:3072
	v_cvt_pk_bf16_f32 v102, v102, v103
	v_cvt_pk_bf16_f32 v103, v104, v105
	v_cvt_pk_bf16_f32 v106, v106, v107
	v_cvt_pk_bf16_f32 v107, v108, v109
	v_cvt_pk_bf16_f32 v110, v110, v111
	v_cvt_pk_bf16_f32 v111, v112, v113
	v_cvt_pk_bf16_f32 v114, v114, v115
	v_cvt_pk_bf16_f32 v115, v116, v117
	global_store_dwordx2 v214, v[102:103], s[70:71] offset:0
	global_store_dwordx2 v214, v[106:107], s[70:71] offset:512
	global_store_dwordx2 v214, v[110:111], s[70:71] offset:1024
	global_store_dwordx2 v214, v[114:115], s[70:71] offset:1536
	s_waitcnt vmcnt(48)
	v_pk_add_f32 v[76:77], v[118:119], v[120:121]
	v_pk_add_f32 v[136:137], v[122:123], v[124:125]
	v_pk_add_f32 v[138:139], v[144:145], v[146:147]
	v_pk_add_f32 v[208:209], v[148:149], v[150:151]
	v_pk_add_f32 v[76:77], v[76:77], v[136:137]
	v_pk_add_f32 v[138:139], v[138:139], v[208:209]
	v_pk_add_f32 v[76:77], v[76:77], v[138:139]
	v_add_f32_e32 v131, v76, v77
	s_nop 1
	v_add_f32_dpp v131, v131, v131 quad_perm:[1,0,3,2] row_mask:0xf bank_mask:0xf bound_ctrl:1
	s_nop 1
	v_add_f32_dpp v131, v131, v131 quad_perm:[2,3,0,1] row_mask:0xf bank_mask:0xf bound_ctrl:1
	s_nop 1
	v_add_f32_dpp v131, v131, v131 row_half_mirror row_mask:0xf bank_mask:0xf bound_ctrl:1
	s_nop 1
	v_add_f32_dpp v131, v131, v131 row_mirror row_mask:0xf bank_mask:0xf bound_ctrl:1
	s_nop 1
	v_readlane_b32 s56, v131, 0
	v_readlane_b32 s57, v131, 16
	v_readlane_b32 s58, v131, 32
	v_readlane_b32 s59, v131, 48
	v_mov_b32_e32 v222, s57
	v_mov_b32_e32 v223, s59
	v_add_f32_e32 v222, s56, v222
	v_add_f32_e32 v223, s58, v223
	v_add_f32_e32 v131, v222, v223
	v_mul_f32_e32 v216, 0x3a800000, v131
	v_pk_add_f32 v[118:119], v[118:119], v[216:217] op_sel_hi:[1,0] neg_lo:[0,1] neg_hi:[0,1]
	v_pk_add_f32 v[120:121], v[120:121], v[216:217] op_sel_hi:[1,0] neg_lo:[0,1] neg_hi:[0,1]
	v_pk_add_f32 v[122:123], v[122:123], v[216:217] op_sel_hi:[1,0] neg_lo:[0,1] neg_hi:[0,1]
	v_pk_add_f32 v[124:125], v[124:125], v[216:217] op_sel_hi:[1,0] neg_lo:[0,1] neg_hi:[0,1]
	v_pk_add_f32 v[144:145], v[144:145], v[216:217] op_sel_hi:[1,0] neg_lo:[0,1] neg_hi:[0,1]
	v_pk_add_f32 v[146:147], v[146:147], v[216:217] op_sel_hi:[1,0] neg_lo:[0,1] neg_hi:[0,1]
	v_pk_add_f32 v[148:149], v[148:149], v[216:217] op_sel_hi:[1,0] neg_lo:[0,1] neg_hi:[0,1]
	v_pk_add_f32 v[150:151], v[150:151], v[216:217] op_sel_hi:[1,0] neg_lo:[0,1] neg_hi:[0,1]
	v_pk_mul_f32 v[76:77], v[118:119], v[118:119]
	v_pk_mul_f32 v[136:137], v[120:121], v[120:121]
	v_add_f32_e32 v133, v76, v77
	v_add_f32_e32 v133, v136, v133
	v_add_f32_e32 v133, v137, v133
	v_pk_mul_f32 v[76:77], v[122:123], v[122:123]
	v_pk_mul_f32 v[136:137], v[124:125], v[124:125]
	v_add_f32_e32 v133, v76, v133
	v_add_f32_e32 v133, v77, v133
	v_add_f32_e32 v133, v136, v133
	v_add_f32_e32 v133, v137, v133
	v_pk_mul_f32 v[76:77], v[144:145], v[144:145]
	v_pk_mul_f32 v[136:137], v[146:147], v[146:147]
	v_add_f32_e32 v133, v76, v133
	v_add_f32_e32 v133, v77, v133
	v_add_f32_e32 v133, v136, v133
	v_add_f32_e32 v133, v137, v133
	v_pk_mul_f32 v[76:77], v[148:149], v[148:149]
	v_pk_mul_f32 v[136:137], v[150:151], v[150:151]
	v_add_f32_e32 v133, v76, v133
	v_add_f32_e32 v133, v77, v133
	v_add_f32_e32 v133, v136, v133
	v_add_f32_e32 v133, v137, v133
	s_nop 1
	v_add_f32_dpp v133, v133, v133 quad_perm:[1,0,3,2] row_mask:0xf bank_mask:0xf bound_ctrl:1
	s_nop 1
	v_add_f32_dpp v133, v133, v133 quad_perm:[2,3,0,1] row_mask:0xf bank_mask:0xf bound_ctrl:1
	s_nop 1
	v_add_f32_dpp v133, v133, v133 row_half_mirror row_mask:0xf bank_mask:0xf bound_ctrl:1
	s_nop 1
	v_add_f32_dpp v133, v133, v133 row_mirror row_mask:0xf bank_mask:0xf bound_ctrl:1
	s_nop 1
	v_readlane_b32 s56, v133, 0
	v_readlane_b32 s57, v133, 16
	v_readlane_b32 s58, v133, 32
	v_readlane_b32 s59, v133, 48
	v_mov_b32_e32 v222, s57
	v_mov_b32_e32 v223, s59
	v_add_f32_e32 v222, s56, v222
	v_add_f32_e32 v223, s58, v223
	v_add_f32_e32 v133, v222, v223
	v_fmamk_f32 v133, v133, 0x3a800000, v215
	v_cmp_gt_f32_e32 vcc, s33, v133
	v_mul_f32_e32 v222, 0x4b800000, v133
	s_nop 0
	v_cndmask_b32_e32 v133, v133, v222, vcc
	v_rsq_f32_e32 v133, v133
	s_nop 0
	v_mul_f32_e32 v222, 0x45800000, v133
	v_cndmask_b32_e32 v220, v133, v222, vcc
	v_pk_mul_f32 v[118:119], v[118:119], v[220:221] op_sel_hi:[1,0]
	v_pk_mul_f32 v[120:121], v[120:121], v[220:221] op_sel_hi:[1,0]
	v_pk_mul_f32 v[122:123], v[122:123], v[220:221] op_sel_hi:[1,0]
	v_pk_mul_f32 v[124:125], v[124:125], v[220:221] op_sel_hi:[1,0]
	v_pk_mul_f32 v[144:145], v[144:145], v[220:221] op_sel_hi:[1,0]
	v_pk_mul_f32 v[146:147], v[146:147], v[220:221] op_sel_hi:[1,0]
	v_pk_mul_f32 v[148:149], v[148:149], v[220:221] op_sel_hi:[1,0]
	v_pk_mul_f32 v[150:151], v[150:151], v[220:221] op_sel_hi:[1,0]
	v_pk_fma_f32 v[118:119], v[184:185], v[118:119], v[200:201]
	v_pk_fma_f32 v[120:121], v[186:187], v[120:121], v[202:203]
	v_pk_fma_f32 v[122:123], v[188:189], v[122:123], v[204:205]
	v_pk_fma_f32 v[124:125], v[190:191], v[124:125], v[206:207]
	v_pk_fma_f32 v[144:145], v[192:193], v[144:145], v[226:227]
	v_pk_fma_f32 v[146:147], v[194:195], v[146:147], v[228:229]
	v_pk_fma_f32 v[148:149], v[196:197], v[148:149], v[230:231]
	v_pk_fma_f32 v[150:151], v[198:199], v[150:151], v[232:233]
	global_store_dwordx4 v212, v[118:121], s[52:53] offset:0
	global_store_dwordx4 v212, v[122:125], s[52:53] offset:1024
	global_store_dwordx4 v212, v[144:147], s[52:53] offset:2048
	global_store_dwordx4 v212, v[148:151], s[52:53] offset:3072
	v_cvt_pk_bf16_f32 v118, v118, v119
	v_cvt_pk_bf16_f32 v119, v120, v121
	v_cvt_pk_bf16_f32 v122, v122, v123
	v_cvt_pk_bf16_f32 v123, v124, v125
	v_cvt_pk_bf16_f32 v144, v144, v145
	v_cvt_pk_bf16_f32 v145, v146, v147
	v_cvt_pk_bf16_f32 v148, v148, v149
	v_cvt_pk_bf16_f32 v149, v150, v151
	global_store_dwordx2 v214, v[118:119], s[70:71] offset:2048
	global_store_dwordx2 v214, v[122:123], s[70:71] offset:2560
	global_store_dwordx2 v214, v[144:145], s[70:71] offset:3072
	global_store_dwordx2 v214, v[148:149], s[70:71] offset:3584
	s_waitcnt vmcnt(52)
	v_pk_add_f32 v[76:77], v[152:153], v[154:155]
	v_pk_add_f32 v[136:137], v[156:157], v[158:159]
	v_pk_add_f32 v[138:139], v[160:161], v[162:163]
	v_pk_add_f32 v[208:209], v[164:165], v[166:167]
	v_pk_add_f32 v[76:77], v[76:77], v[136:137]
	v_pk_add_f32 v[138:139], v[138:139], v[208:209]
	v_pk_add_f32 v[76:77], v[76:77], v[138:139]
	v_add_f32_e32 v131, v76, v77
	s_nop 1
	v_add_f32_dpp v131, v131, v131 quad_perm:[1,0,3,2] row_mask:0xf bank_mask:0xf bound_ctrl:1
	s_nop 1
	v_add_f32_dpp v131, v131, v131 quad_perm:[2,3,0,1] row_mask:0xf bank_mask:0xf bound_ctrl:1
	s_nop 1
	v_add_f32_dpp v131, v131, v131 row_half_mirror row_mask:0xf bank_mask:0xf bound_ctrl:1
	s_nop 1
	v_add_f32_dpp v131, v131, v131 row_mirror row_mask:0xf bank_mask:0xf bound_ctrl:1
	s_nop 1
	v_readlane_b32 s56, v131, 0
	v_readlane_b32 s57, v131, 16
	v_readlane_b32 s58, v131, 32
	v_readlane_b32 s59, v131, 48
	v_mov_b32_e32 v222, s57
	v_mov_b32_e32 v223, s59
	v_add_f32_e32 v222, s56, v222
	v_add_f32_e32 v223, s58, v223
	v_add_f32_e32 v131, v222, v223
	v_mul_f32_e32 v216, 0x3a800000, v131
	v_pk_add_f32 v[152:153], v[152:153], v[216:217] op_sel_hi:[1,0] neg_lo:[0,1] neg_hi:[0,1]
	v_pk_add_f32 v[154:155], v[154:155], v[216:217] op_sel_hi:[1,0] neg_lo:[0,1] neg_hi:[0,1]
	v_pk_add_f32 v[156:157], v[156:157], v[216:217] op_sel_hi:[1,0] neg_lo:[0,1] neg_hi:[0,1]
	v_pk_add_f32 v[158:159], v[158:159], v[216:217] op_sel_hi:[1,0] neg_lo:[0,1] neg_hi:[0,1]
	v_pk_add_f32 v[160:161], v[160:161], v[216:217] op_sel_hi:[1,0] neg_lo:[0,1] neg_hi:[0,1]
	v_pk_add_f32 v[162:163], v[162:163], v[216:217] op_sel_hi:[1,0] neg_lo:[0,1] neg_hi:[0,1]
	v_pk_add_f32 v[164:165], v[164:165], v[216:217] op_sel_hi:[1,0] neg_lo:[0,1] neg_hi:[0,1]
	v_pk_add_f32 v[166:167], v[166:167], v[216:217] op_sel_hi:[1,0] neg_lo:[0,1] neg_hi:[0,1]
	v_pk_mul_f32 v[76:77], v[152:153], v[152:153]
	v_pk_mul_f32 v[136:137], v[154:155], v[154:155]
	v_add_f32_e32 v133, v76, v77
	v_add_f32_e32 v133, v136, v133
	v_add_f32_e32 v133, v137, v133
	v_pk_mul_f32 v[76:77], v[156:157], v[156:157]
	v_pk_mul_f32 v[136:137], v[158:159], v[158:159]
	v_add_f32_e32 v133, v76, v133
	v_add_f32_e32 v133, v77, v133
	v_add_f32_e32 v133, v136, v133
	v_add_f32_e32 v133, v137, v133
	v_pk_mul_f32 v[76:77], v[160:161], v[160:161]
	v_pk_mul_f32 v[136:137], v[162:163], v[162:163]
	v_add_f32_e32 v133, v76, v133
	v_add_f32_e32 v133, v77, v133
	v_add_f32_e32 v133, v136, v133
	v_add_f32_e32 v133, v137, v133
	v_pk_mul_f32 v[76:77], v[164:165], v[164:165]
	v_pk_mul_f32 v[136:137], v[166:167], v[166:167]
	v_add_f32_e32 v133, v76, v133
	v_add_f32_e32 v133, v77, v133
	v_add_f32_e32 v133, v136, v133
	v_add_f32_e32 v133, v137, v133
	s_nop 1
	v_add_f32_dpp v133, v133, v133 quad_perm:[1,0,3,2] row_mask:0xf bank_mask:0xf bound_ctrl:1
	s_nop 1
	v_add_f32_dpp v133, v133, v133 quad_perm:[2,3,0,1] row_mask:0xf bank_mask:0xf bound_ctrl:1
	s_nop 1
	v_add_f32_dpp v133, v133, v133 row_half_mirror row_mask:0xf bank_mask:0xf bound_ctrl:1
	s_nop 1
	v_add_f32_dpp v133, v133, v133 row_mirror row_mask:0xf bank_mask:0xf bound_ctrl:1
	s_nop 1
	v_readlane_b32 s56, v133, 0
	v_readlane_b32 s57, v133, 16
	v_readlane_b32 s58, v133, 32
	v_readlane_b32 s59, v133, 48
	v_mov_b32_e32 v222, s57
	v_mov_b32_e32 v223, s59
	v_add_f32_e32 v222, s56, v222
	v_add_f32_e32 v223, s58, v223
	v_add_f32_e32 v133, v222, v223
	v_fmamk_f32 v133, v133, 0x3a800000, v215
	v_cmp_gt_f32_e32 vcc, s33, v133
	v_mul_f32_e32 v222, 0x4b800000, v133
	s_nop 0
	v_cndmask_b32_e32 v133, v133, v222, vcc
	v_rsq_f32_e32 v133, v133
	s_nop 0
	v_mul_f32_e32 v222, 0x45800000, v133
	v_cndmask_b32_e32 v220, v133, v222, vcc
	v_pk_mul_f32 v[152:153], v[152:153], v[220:221] op_sel_hi:[1,0]
	v_pk_mul_f32 v[154:155], v[154:155], v[220:221] op_sel_hi:[1,0]
	v_pk_mul_f32 v[156:157], v[156:157], v[220:221] op_sel_hi:[1,0]
	v_pk_mul_f32 v[158:159], v[158:159], v[220:221] op_sel_hi:[1,0]
	v_pk_mul_f32 v[160:161], v[160:161], v[220:221] op_sel_hi:[1,0]
	v_pk_mul_f32 v[162:163], v[162:163], v[220:221] op_sel_hi:[1,0]
	v_pk_mul_f32 v[164:165], v[164:165], v[220:221] op_sel_hi:[1,0]
	v_pk_mul_f32 v[166:167], v[166:167], v[220:221] op_sel_hi:[1,0]
	v_pk_fma_f32 v[152:153], v[184:185], v[152:153], v[200:201]
	v_pk_fma_f32 v[154:155], v[186:187], v[154:155], v[202:203]
	v_pk_fma_f32 v[156:157], v[188:189], v[156:157], v[204:205]
	v_pk_fma_f32 v[158:159], v[190:191], v[158:159], v[206:207]
	v_pk_fma_f32 v[160:161], v[192:193], v[160:161], v[226:227]
	v_pk_fma_f32 v[162:163], v[194:195], v[162:163], v[228:229]
	v_pk_fma_f32 v[164:165], v[196:197], v[164:165], v[230:231]
	v_pk_fma_f32 v[166:167], v[198:199], v[166:167], v[232:233]
	global_store_dwordx4 v212, v[152:155], s[62:63] offset:0
	global_store_dwordx4 v212, v[156:159], s[62:63] offset:1024
	global_store_dwordx4 v212, v[160:163], s[62:63] offset:2048
	global_store_dwordx4 v212, v[164:167], s[62:63] offset:3072
	v_cvt_pk_bf16_f32 v152, v152, v153
	v_cvt_pk_bf16_f32 v153, v154, v155
	v_cvt_pk_bf16_f32 v156, v156, v157
	v_cvt_pk_bf16_f32 v157, v158, v159
	v_cvt_pk_bf16_f32 v160, v160, v161
	v_cvt_pk_bf16_f32 v161, v162, v163
	v_cvt_pk_bf16_f32 v164, v164, v165
	v_cvt_pk_bf16_f32 v165, v166, v167
	global_store_dwordx2 v214, v[152:153], s[72:73] offset:0
	global_store_dwordx2 v214, v[156:157], s[72:73] offset:512
	global_store_dwordx2 v214, v[160:161], s[72:73] offset:1024
	global_store_dwordx2 v214, v[164:165], s[72:73] offset:1536
	s_waitcnt vmcnt(56)
	v_pk_add_f32 v[76:77], v[168:169], v[170:171]
	v_pk_add_f32 v[136:137], v[172:173], v[174:175]
	v_pk_add_f32 v[138:139], v[176:177], v[178:179]
	v_pk_add_f32 v[208:209], v[180:181], v[182:183]
	v_pk_add_f32 v[76:77], v[76:77], v[136:137]
	v_pk_add_f32 v[138:139], v[138:139], v[208:209]
	v_pk_add_f32 v[76:77], v[76:77], v[138:139]
	v_add_f32_e32 v131, v76, v77
	s_nop 1
	v_add_f32_dpp v131, v131, v131 quad_perm:[1,0,3,2] row_mask:0xf bank_mask:0xf bound_ctrl:1
	s_nop 1
	v_add_f32_dpp v131, v131, v131 quad_perm:[2,3,0,1] row_mask:0xf bank_mask:0xf bound_ctrl:1
	s_nop 1
	v_add_f32_dpp v131, v131, v131 row_half_mirror row_mask:0xf bank_mask:0xf bound_ctrl:1
	s_nop 1
	v_add_f32_dpp v131, v131, v131 row_mirror row_mask:0xf bank_mask:0xf bound_ctrl:1
	s_nop 1
	v_readlane_b32 s56, v131, 0
	v_readlane_b32 s57, v131, 16
	v_readlane_b32 s58, v131, 32
	v_readlane_b32 s59, v131, 48
	v_mov_b32_e32 v222, s57
	v_mov_b32_e32 v223, s59
	v_add_f32_e32 v222, s56, v222
	v_add_f32_e32 v223, s58, v223
	v_add_f32_e32 v131, v222, v223
	v_mul_f32_e32 v216, 0x3a800000, v131
	v_pk_add_f32 v[168:169], v[168:169], v[216:217] op_sel_hi:[1,0] neg_lo:[0,1] neg_hi:[0,1]
	v_pk_add_f32 v[170:171], v[170:171], v[216:217] op_sel_hi:[1,0] neg_lo:[0,1] neg_hi:[0,1]
	v_pk_add_f32 v[172:173], v[172:173], v[216:217] op_sel_hi:[1,0] neg_lo:[0,1] neg_hi:[0,1]
	v_pk_add_f32 v[174:175], v[174:175], v[216:217] op_sel_hi:[1,0] neg_lo:[0,1] neg_hi:[0,1]
	v_pk_add_f32 v[176:177], v[176:177], v[216:217] op_sel_hi:[1,0] neg_lo:[0,1] neg_hi:[0,1]
	v_pk_add_f32 v[178:179], v[178:179], v[216:217] op_sel_hi:[1,0] neg_lo:[0,1] neg_hi:[0,1]
	v_pk_add_f32 v[180:181], v[180:181], v[216:217] op_sel_hi:[1,0] neg_lo:[0,1] neg_hi:[0,1]
	v_pk_add_f32 v[182:183], v[182:183], v[216:217] op_sel_hi:[1,0] neg_lo:[0,1] neg_hi:[0,1]
	v_pk_mul_f32 v[76:77], v[168:169], v[168:169]
	v_pk_mul_f32 v[136:137], v[170:171], v[170:171]
	v_add_f32_e32 v133, v76, v77
	v_add_f32_e32 v133, v136, v133
	v_add_f32_e32 v133, v137, v133
	v_pk_mul_f32 v[76:77], v[172:173], v[172:173]
	v_pk_mul_f32 v[136:137], v[174:175], v[174:175]
	v_add_f32_e32 v133, v76, v133
	v_add_f32_e32 v133, v77, v133
	v_add_f32_e32 v133, v136, v133
	v_add_f32_e32 v133, v137, v133
	v_pk_mul_f32 v[76:77], v[176:177], v[176:177]
	v_pk_mul_f32 v[136:137], v[178:179], v[178:179]
	v_add_f32_e32 v133, v76, v133
	v_add_f32_e32 v133, v77, v133
	v_add_f32_e32 v133, v136, v133
	v_add_f32_e32 v133, v137, v133
	v_pk_mul_f32 v[76:77], v[180:181], v[180:181]
	v_pk_mul_f32 v[136:137], v[182:183], v[182:183]
	v_add_f32_e32 v133, v76, v133
	v_add_f32_e32 v133, v77, v133
	v_add_f32_e32 v133, v136, v133
	v_add_f32_e32 v133, v137, v133
	s_nop 1
	v_add_f32_dpp v133, v133, v133 quad_perm:[1,0,3,2] row_mask:0xf bank_mask:0xf bound_ctrl:1
	s_nop 1
	v_add_f32_dpp v133, v133, v133 quad_perm:[2,3,0,1] row_mask:0xf bank_mask:0xf bound_ctrl:1
	s_nop 1
	v_add_f32_dpp v133, v133, v133 row_half_mirror row_mask:0xf bank_mask:0xf bound_ctrl:1
	s_nop 1
	v_add_f32_dpp v133, v133, v133 row_mirror row_mask:0xf bank_mask:0xf bound_ctrl:1
	s_nop 1
	v_readlane_b32 s56, v133, 0
	v_readlane_b32 s57, v133, 16
	v_readlane_b32 s58, v133, 32
	v_readlane_b32 s59, v133, 48
	v_mov_b32_e32 v222, s57
	v_mov_b32_e32 v223, s59
	v_add_f32_e32 v222, s56, v222
	v_add_f32_e32 v223, s58, v223
	v_add_f32_e32 v133, v222, v223
	v_fmamk_f32 v133, v133, 0x3a800000, v215
	v_cmp_gt_f32_e32 vcc, s33, v133
	v_mul_f32_e32 v222, 0x4b800000, v133
	s_nop 0
	v_cndmask_b32_e32 v133, v133, v222, vcc
	v_rsq_f32_e32 v133, v133
	s_nop 0
	v_mul_f32_e32 v222, 0x45800000, v133
	v_cndmask_b32_e32 v220, v133, v222, vcc
	v_pk_mul_f32 v[168:169], v[168:169], v[220:221] op_sel_hi:[1,0]
	v_pk_mul_f32 v[170:171], v[170:171], v[220:221] op_sel_hi:[1,0]
	v_pk_mul_f32 v[172:173], v[172:173], v[220:221] op_sel_hi:[1,0]
	v_pk_mul_f32 v[174:175], v[174:175], v[220:221] op_sel_hi:[1,0]
	v_pk_mul_f32 v[176:177], v[176:177], v[220:221] op_sel_hi:[1,0]
	v_pk_mul_f32 v[178:179], v[178:179], v[220:221] op_sel_hi:[1,0]
	v_pk_mul_f32 v[180:181], v[180:181], v[220:221] op_sel_hi:[1,0]
	v_pk_mul_f32 v[182:183], v[182:183], v[220:221] op_sel_hi:[1,0]
	v_pk_fma_f32 v[168:169], v[184:185], v[168:169], v[200:201]
	v_pk_fma_f32 v[170:171], v[186:187], v[170:171], v[202:203]
	v_pk_fma_f32 v[172:173], v[188:189], v[172:173], v[204:205]
	v_pk_fma_f32 v[174:175], v[190:191], v[174:175], v[206:207]
	v_pk_fma_f32 v[176:177], v[192:193], v[176:177], v[226:227]
	v_pk_fma_f32 v[178:179], v[194:195], v[178:179], v[228:229]
	v_pk_fma_f32 v[180:181], v[196:197], v[180:181], v[230:231]
	v_pk_fma_f32 v[182:183], v[198:199], v[182:183], v[232:233]
	global_store_dwordx4 v212, v[168:171], s[64:65] offset:0
	global_store_dwordx4 v212, v[172:175], s[64:65] offset:1024
	global_store_dwordx4 v212, v[176:179], s[64:65] offset:2048
	global_store_dwordx4 v212, v[180:183], s[64:65] offset:3072
	v_cvt_pk_bf16_f32 v168, v168, v169
	v_cvt_pk_bf16_f32 v169, v170, v171
	v_cvt_pk_bf16_f32 v172, v172, v173
	v_cvt_pk_bf16_f32 v173, v174, v175
	v_cvt_pk_bf16_f32 v176, v176, v177
	v_cvt_pk_bf16_f32 v177, v178, v179
	v_cvt_pk_bf16_f32 v180, v180, v181
	v_cvt_pk_bf16_f32 v181, v182, v183
	global_store_dwordx2 v214, v[168:169], s[72:73] offset:2048
	global_store_dwordx2 v214, v[172:173], s[72:73] offset:2560
	global_store_dwordx2 v214, v[176:177], s[72:73] offset:3072
	global_store_dwordx2 v214, v[180:181], s[72:73] offset:3584
	s_xor_b64 s[20:21], exec, -1
	s_branch .LBB0_1609
